# ds_read_b128 hoist also applied to the upproj/outproj/small GEMM k-loops (109 more reads moved)
# baseline (speedup 1.0000x reference)
; DEV int opaque_tid() { int t = threadIdx.x; asm volatile("" : "+v"(t)); return t; }
;     ...
;   const int tid = opaque_tid(), lane = tid & 63, h = lane >> 5, r = lane & 31;
;   const int nk = K >> 6;
;   const int cch = (tid & 7) ^ ((tid >> 4) & 7);
;   const u16* ga = A + (size_t)(tid >> 3) * lda + cch * 8;
;   const u16* gb = Bt + (size_t)(tid >> 3) * ldb + cch * 8;
;   char* lds_t = smem + tid * 16;
;   auto issue_piece = [&](int kt, int pc) {
;     char* st = lds_t + (kt % NSTG) * STAGE;
;     if (pc < 4)
;       __builtin_amdgcn_global_load_lds((const unsigned*)(ga + (size_t)(64 * pc) * lda + (size_t)kt * ksa), (unsigned __attribute__((address_space(3)))*)(st + pc * 8192), 16, 0, 0);
;     else
;       __builtin_amdgcn_global_load_lds((const unsigned*)(gb + (size_t)(64 * (pc - 4)) * ldb + (size_t)kt * ksb), (unsigned __attribute__((address_space(3)))*)(st + ABYTES + (pc - 4) * 8192), 16, 0, 0);
;   };
;   const int x = (r >> 1) & 7;
;   int xo[4];
; #pragma unroll
;   for (int s = 0; s < 4; ++s) xo[s] = (((2 * s + h) ^ x) << 4);
;   asm volatile("s_waitcnt vmcnt(0)" ::: "memory");
; #pragma unroll
;   for (int d = 0; d < DIST; ++d)
; #pragma unroll
;     for (int pc = 0; pc < NLD; ++pc) issue_piece(d, pc);
; DEV void phase_outproj(const Params& p, int l, int hf, char* smem) {
;     ...
;   for (int t = blockIdx.x; t < nslots; t += gridDim.x) {
;     int mq, nt;
;     if (!tile_decode(t, 64, 8, 4, mq, nt)) continue;
;     const int mt = (mq >> 5) * 33 + 1 + (mq & 31);
;     f32x16 acc[2][2];
; #pragma unroll
;     for (int i = 0; i < 2; ++i)
; #pragma unroll
;       for (int j = 0; j < 2; ++j)
; #pragma unroll
;         for (int e = 0; e < 16; ++e) acc[i][j][e] = 0.f;
;     float4 xpre[2][2][4];
;     auto load_x = [&]() {
; #pragma unroll
;       for (int j = 0; j < 2; ++j) {
;         const int m = mt * 256 + wm * 64 + 32 * j + r;
;         const int bl = m / TP, tp = m - bl * TP;
;         const int b = hf * 2 + bl;
;         const float* src = (tp < CTXL) ? p.ctx + ((size_t)b * CTXL + tp) * DM : xs + ((size_t)b * SEQ + (tp - CTXL)) * DM;
; #pragma unroll
;         for (int i = 0; i < 2; ++i)
; #pragma unroll
;           for (int g4 = 0; g4 < 4; ++g4) xpre[i][j][g4] = *(const float4*)(src + nt * 128 + wn * 64 + 32 * i + 8 * g4 + 4 * h);
;       }
;     };
.LBB0_19:
	s_lshl_b32 s3, s20, 6
	s_ashr_i32 s2, s20, 3
	s_and_b32 s3, s3, 0x1c0
	s_add_i32 s2, s3, s2
	s_ashr_i32 s3, s2, 31
	s_lshr_b32 s3, s3, 27
	s_add_i32 s3, s2, s3
	s_ashr_i32 s12, s3, 5
	s_andn2_b32 s3, s3, 31
	s_sub_i32 s3, s2, s3
	s_ashr_i32 s2, s3, 31
	s_lshr_b32 s2, s2, 30
	s_lshl_b32 s12, s12, 2
	s_add_i32 s13, s3, s2
	s_add_i32 s3, s3, s12
	s_and_b32 s12, s13, -4
	s_sub_i32 s3, s3, s12
	s_ashr_i32 s12, s3, 5
	s_and_b32 s3, s3, 31
	s_mul_i32 s12, s12, 33
	s_add_i32 s3, s3, s12
	s_add_i32 s12, s3, 1
	s_ashr_i32 s2, s13, 2
	s_ashr_i32 s13, s12, 31
	s_lshl_b64 s[22:23], s[12:13], 19
	s_add_u32 s22, s14, s22
	v_mov_b32_e32 v6, v147
	s_addc_u32 s23, s15, s23
	s_ashr_i32 s3, s2, 31
	s_lshl_b64 s[24:25], s[2:3], 18
	v_lshrrev_b32_e32 v0, 4, v6
	v_xor_b32_e32 v4, v0, v6
	v_ashrrev_i32_e32 v0, 3, v6
	s_add_u32 s24, s16, s24
	v_ashrrev_i32_e32 v1, 31, v0
	s_addc_u32 s25, s17, s25
	v_lshlrev_b64 v[0:1], 11, v[0:1]
	v_lshlrev_b32_e32 v4, 4, v4
	v_lshl_add_u32 v205, v6, 4, 0
	v_lshl_add_u64 v[2:3], s[24:25], 0, v[0:1]
	v_lshl_add_u64 v[0:1], s[22:23], 0, v[0:1]
	v_and_b32_e32 v144, 0x70, v4
	v_readfirstlane_b32 s41, v205
	v_add_u32_e32 v204, 0x2000, v205
	v_lshl_add_u64 v[140:141], v[0:1], 0, v[144:145]
	s_waitcnt vmcnt(0)
	s_mov_b32 m0, s41
	v_readfirstlane_b32 s37, v204
	v_add_u32_e32 v203, 0x4000, v205
	global_load_lds_dwordx4 v[140:141], off
	v_lshl_add_u64 v[0:1], v[140:141], 0, s[56:57]
	s_mov_b32 m0, s37
	v_readfirstlane_b32 s31, v203
	v_add_u32_e32 v200, 0x6000, v205
	v_add_u32_e32 v195, 0x8000, v205
	global_load_lds_dwordx4 v[0:1], off
	v_lshl_add_u64 v[0:1], v[140:141], 0, s[82:83]
	s_mov_b32 m0, s31
	v_readfirstlane_b32 s28, v200
	global_load_lds_dwordx4 v[0:1], off
	v_lshl_add_u64 v[0:1], v[140:141], 0, s[92:93]
	s_mov_b32 m0, s28
	v_readfirstlane_b32 s27, v195
	v_add_u32_e32 v197, 0xa000, v205
	v_lshl_add_u64 v[138:139], v[2:3], 0, v[144:145]
	global_load_lds_dwordx4 v[0:1], off
	s_mov_b32 m0, s27
	v_readfirstlane_b32 s26, v197
	v_add_u32_e32 v193, 0xc000, v205
	global_load_lds_dwordx4 v[138:139], off
	v_lshl_add_u64 v[0:1], v[138:139], 0, s[56:57]
	s_mov_b32 m0, s26
	v_readfirstlane_b32 s25, v193
	v_add_u32_e32 v192, 0xe000, v205
	global_load_lds_dwordx4 v[0:1], off
	v_lshl_add_u64 v[2:3], v[140:141], 0, s[62:63]
	s_mov_b32 m0, s25
	v_readfirstlane_b32 s24, v192
	v_add_u32_e32 v191, 0x10000, v205
	global_load_lds_dwordx4 v[2:3], off
	v_lshl_add_u64 v[2:3], v[140:141], 0, s[64:65]
	s_mov_b32 m0, s24
	v_readfirstlane_b32 s23, v191
	v_add_u32_e32 v190, 0x12000, v205
	global_load_lds_dwordx4 v[2:3], off
	v_lshl_add_u64 v[2:3], v[140:141], 0, s[66:67]
	s_mov_b32 m0, s23
	v_readfirstlane_b32 s22, v190
	v_add_u32_e32 v4, 0x14000, v205
	global_load_lds_dwordx4 v[2:3], off
	v_lshl_add_u64 v[2:3], v[140:141], 0, s[76:77]
	s_mov_b32 m0, s22
	v_readfirstlane_b32 s21, v4
	global_load_lds_dwordx4 v[2:3], off
	v_add_u32_e32 v2, 0x16000, v205
	v_lshl_add_u64 v[0:1], v[138:139], 0, s[62:63]
	s_mov_b32 m0, s21
	v_readfirstlane_b32 s13, v2
	s_lshl_b32 s12, s12, 8
	global_load_lds_dwordx4 v[0:1], off
	v_lshl_add_u64 v[0:1], v[138:139], 0, s[64:65]
	s_mov_b32 m0, s13
	v_add_u32_e32 v154, s12, v149
	global_load_lds_dwordx4 v[0:1], off
	v_mul_hi_i32 v0, v154, s72
	v_lshrrev_b32_e32 v1, 31, v0
	v_ashrrev_i32_e32 v0, 11, v0
	v_add_u32_e32 v0, v0, v1
	v_mad_i32_i24 v136, v0, s73, v154
	s_movk_i32 s29, 0x100
	v_add_u32_e32 v134, s19, v0
	v_cmp_gt_i32_e32 vcc, s29, v136
	v_ashrrev_i32_e32 v135, 31, v134
	v_add_u32_e32 v144, 0xffffff00, v136
	v_ashrrev_i32_e32 v137, 31, v136
	v_cndmask_b32_e64 v4, 25, 20, vcc
	v_cndmask_b32_e32 v1, v152, v167, vcc
	v_cndmask_b32_e32 v0, v153, v168, vcc
	v_cndmask_b32_e32 v3, 0, v137, vcc
	v_cndmask_b32_e32 v2, v144, v136, vcc
	v_lshlrev_b64 v[4:5], v4, v[134:135]
	s_lshl_b32 s2, s2, 7
	v_lshl_add_u64 v[0:1], v[0:1], 0, v[4:5]
	v_lshlrev_b64 v[2:3], 12, v[2:3]
	s_ashr_i32 s3, s2, 31
	v_lshl_add_u64 v[0:1], v[0:1], 0, v[2:3]
	s_lshl_b64 s[42:43], s[2:3], 2
	v_lshl_add_u64 v[0:1], v[0:1], 0, s[42:43]
	v_lshl_add_u64 v[0:1], v[0:1], 0, v[130:131]
	v_lshl_add_u64 v[0:1], v[0:1], 0, v[132:133]
	global_load_dwordx4 v[124:127], v[0:1], off
	global_load_dwordx4 v[120:123], v[0:1], off offset:32
	global_load_dwordx4 v[116:119], v[0:1], off offset:64
	global_load_dwordx4 v[112:115], v[0:1], off offset:96
	global_load_dwordx4 v[108:111], v[0:1], off offset:128
	global_load_dwordx4 v[104:107], v[0:1], off offset:160
	global_load_dwordx4 v[100:103], v[0:1], off offset:192
	global_load_dwordx4 v[96:99], v[0:1], off offset:224
	v_add_u32_e32 v0, s12, v150
	v_mul_hi_i32 v1, v0, s72
	v_lshrrev_b32_e32 v2, 31, v1
	v_ashrrev_i32_e32 v1, 11, v1
	v_add_u32_e32 v1, v1, v2
	v_mad_i32_i24 v4, v1, s73, v0
	v_add_u32_e32 v0, s19, v1
	v_add_u32_e32 v7, 0xffffff00, v4
	v_cmp_gt_i32_e32 vcc, s29, v4
	v_ashrrev_i32_e32 v1, 31, v0
	v_ashrrev_i32_e32 v5, 31, v4
	v_cndmask_b32_e32 v4, v7, v4, vcc
	v_cndmask_b32_e64 v7, 25, 20, vcc
	v_cndmask_b32_e32 v3, v152, v167, vcc
	v_cndmask_b32_e32 v2, v153, v168, vcc
	v_cndmask_b32_e32 v5, 0, v5, vcc
	v_lshlrev_b64 v[0:1], v7, v[0:1]
	v_lshl_add_u64 v[0:1], v[2:3], 0, v[0:1]
	v_lshlrev_b64 v[2:3], 12, v[4:5]
	v_lshl_add_u64 v[0:1], v[0:1], 0, v[2:3]
	v_lshl_add_u64 v[0:1], v[0:1], 0, s[42:43]
	v_lshl_add_u64 v[0:1], v[0:1], 0, v[130:131]
	v_lshl_add_u64 v[0:1], v[0:1], 0, v[132:133]
	global_load_dwordx4 v[92:95], v[0:1], off
	global_load_dwordx4 v[88:91], v[0:1], off offset:32
	global_load_dwordx4 v[84:87], v[0:1], off offset:64
	global_load_dwordx4 v[80:83], v[0:1], off offset:96
	global_load_dwordx4 v[76:79], v[0:1], off offset:128
	global_load_dwordx4 v[72:75], v[0:1], off offset:160
	global_load_dwordx4 v[68:71], v[0:1], off offset:192
	global_load_dwordx4 v[64:67], v[0:1], off offset:224
	v_lshrrev_b32_e32 v0, 5, v6
	v_bfe_u32 v2, v6, 1, 3
	v_bfe_u32 v1, v6, 5, 1
	v_bitop3_b32 v0, v0, v2, 1 bitop3:0x6c
	v_lshlrev_b32_e32 v220, 4, v0
	v_bitop3_b32 v0, v1, v2, 2 bitop3:0x36
	v_lshlrev_b32_e32 v221, 4, v0
	v_bitop3_b32 v0, v1, v2, 4 bitop3:0x36
	v_lshlrev_b32_e32 v224, 4, v0
	v_bitop3_b32 v0, v1, v2, 6 bitop3:0x36
	v_lshlrev_b32_e32 v225, 4, v0
	v_and_b32_e32 v0, 31, v6
	v_or_b32_e32 v1, v0, v148
	v_or_b32_e32 v0, v0, v128
	v_lshlrev_b32_e32 v181, 7, v0
	v_add_u32_e32 v159, 0, v181
	v_add_u32_e32 v155, v159, v220
	v_lshlrev_b32_e32 v222, 7, v1
	s_waitcnt vmcnt(6)
	s_barrier
; #define MFMA(a, b, c) __builtin_amdgcn_mfma_f32_32x32x16_bf16((a), (b), (c), 0, 0, 0)
;     ...
;   for (int kt = 0; kt < nk; ++kt) {
;     if (DIST == 2 && kt + 1 < nk) {
;       if (NLD == 6) asm volatile("s_waitcnt vmcnt(6)" ::: "memory");
;       else if (NLD == 5) asm volatile("s_waitcnt vmcnt(5)" ::: "memory");
;       else asm volatile("s_waitcnt vmcnt(8)" ::: "memory");
;     } else {
;       asm volatile("s_waitcnt vmcnt(0)" ::: "memory");
;     }
;     __builtin_amdgcn_s_barrier();
;     const bool pre = (kt + DIST < nk);
;     const char* base = smem + (kt % NSTG) * STAGE;
;     const char* pa = base + (wrow_act + r) * 128;
;     const char* pw = base + ABYTES + (wrow_w + r) * 128;
;     constexpr int NM = NI * MJ;
;     constexpr int PPS = (NLD + 1) / 2;
; #pragma unroll
;     for (int s = 0; s < 4; ++s) {
;       bf16x8 af[MJ], wf[NI];
; #pragma unroll
;       for (int j = 0; j < MJ; ++j) af[j] = *(const bf16x8*)(pa + j * 32 * 128 + xo[s]);
; #pragma unroll
;       for (int i = 0; i < NI; ++i) wf[i] = *(const bf16x8*)(pw + i * 32 * 128 + xo[s]);
; #pragma unroll
;       for (int m = 0; m < NM; ++m) {
;         const int i = m / MJ, j = m % MJ;
;         acc[i][j] = MFMA(wf[i], af[j], acc[i][j]);
;         if (s < 2 && NM >= PPS) {
;           constexpr int EVERY = (NM / PPS) > 0 ? (NM / PPS) : 1;
;           if ((m + 1) % EVERY == 0) {
;             const int pc = s * PPS + (m + 1) / EVERY - 1;
;             if ((m + 1) / EVERY <= PPS && pc < NLD) {
;               __builtin_amdgcn_sched_barrier(0);
;               if (pre) issue_piece(kt + DIST, pc);
;               __builtin_amdgcn_sched_barrier(0);
;             }
;           }
;         }
;         if (s < 2 && NM < PPS) {
;           const int slot = s * NM + m;
;           __builtin_amdgcn_sched_barrier(0);
; #pragma unroll
;           for (int pc = 0; pc < NLD; ++pc)
;             if ((pc * 2 * NM) / NLD == slot && pre) issue_piece(kt + DIST, pc);
;           __builtin_amdgcn_sched_barrier(0);
;         }
;       }
;     }
;   }
	ds_read_b128 v[0:3], v155 offset:32768
	v_add_u32_e32 v214, 0, v222
	v_add_u32_e32 v156, v214, v220
	ds_read_b128 v[4:7], v156
	s_waitcnt lgkmcnt(0)
	ds_read_b128 v[8:11], v156 offset:4096
	ds_read_b128 v[12:15], v155 offset:36864
	v_mfma_f32_32x32x16_bf16 v[48:63], v[0:3], v[4:7], 0
	v_cmp_lt_i32_e32 vcc, s70, v136
	v_add_u32_e32 v196, 0x18000, v205
	v_lshl_add_u64 v[164:165], v[138:139], 0, s[78:79]
	v_add_u32_e32 v194, 0x20000, v205
	v_readfirstlane_b32 s3, v196
	v_lshl_add_u64 v[16:17], v[140:141], 0, s[78:79]
	s_mov_b32 m0, s3
	s_nop 0
	global_load_lds_dwordx4 v[16:17], off
	s_waitcnt lgkmcnt(0)
	v_mfma_f32_32x32x16_bf16 v[16:31], v[0:3], v[8:11], 0
	v_add_u32_e32 v198, 0x1a000, v205
	s_mov_b64 s[42:43], 0x20100
	v_readfirstlane_b32 s12, v198
	v_lshl_add_u64 v[0:1], v[140:141], 0, s[42:43]
	s_mov_b32 m0, s12
	s_nop 0
	global_load_lds_dwordx4 v[0:1], off
	v_mfma_f32_32x32x16_bf16 v[32:47], v[12:15], v[4:7], 0
	v_add_u32_e32 v199, 0x1c000, v205
	s_mov_b64 s[44:45], 0x40100
	v_readfirstlane_b32 s29, v199
	v_lshl_add_u64 v[0:1], v[140:141], 0, s[44:45]
	s_mov_b32 m0, s29
	s_nop 0
	global_load_lds_dwordx4 v[0:1], off
	v_add_u32_e32 v157, v159, v221
	ds_read_b128 v[160:163], v157 offset:32768
	v_add_u32_e32 v158, v214, v221
	ds_read_b128 v[182:185], v158
	ds_read_b128 v[186:189], v158 offset:4096
	ds_read_b128 v[206:209], v157 offset:36864
	v_mfma_f32_32x32x16_bf16 v[0:15], v[12:15], v[8:11], 0
	s_waitcnt lgkmcnt(0)
	v_mfma_f32_32x32x16_bf16 v[48:63], v[160:163], v[182:185], v[48:63]
	v_add_u32_e32 v201, 0x1e000, v205
	s_mov_b64 s[44:45], 0x60100
	v_readfirstlane_b32 s30, v201
	v_lshl_add_u64 v[210:211], v[140:141], 0, s[44:45]
	s_mov_b32 m0, s30
	s_nop 0
	global_load_lds_dwordx4 v[210:211], off
	v_mfma_f32_32x32x16_bf16 v[16:31], v[160:163], v[186:189], v[16:31]
	v_readfirstlane_b32 s36, v194
	s_mov_b32 m0, s36
	s_nop 0
	global_load_lds_dwordx4 v[164:165], off
	v_mfma_f32_32x32x16_bf16 v[32:47], v[206:209], v[182:185], v[32:47]
	v_add_u32_e32 v202, 0x22000, v205
	v_lshl_add_u64 v[160:161], v[138:139], 0, s[42:43]
	v_readfirstlane_b32 s40, v202
	s_mov_b32 m0, s40
	s_nop 0
	global_load_lds_dwordx4 v[160:161], off
	v_add_u32_e32 v160, v159, v224
	ds_read_b128 v[182:185], v160 offset:32768
	v_add_u32_e32 v162, v214, v224
	v_mfma_f32_32x32x16_bf16 v[0:15], v[206:209], v[186:189], v[0:15]
	ds_read_b128 v[186:189], v162
	ds_read_b128 v[206:209], v162 offset:4096
	ds_read_b128 v[210:213], v160 offset:36864
	v_add_u32_e32 v159, v159, v225
	v_add_u32_e32 v161, v214, v225
	s_add_i32 s42, 0, 0x14000
	v_add_u32_e32 v163, s42, v181
	v_add_u32_e32 v165, v163, v220
	s_mov_b64 s[42:43], 0x180
	s_waitcnt lgkmcnt(0)
	v_mfma_f32_32x32x16_bf16 v[48:63], v[182:185], v[186:189], v[48:63]
	v_lshl_add_u64 v[218:219], v[138:139], 0, s[42:43]
	v_mfma_f32_32x32x16_bf16 v[16:31], v[182:185], v[206:209], v[16:31]
	ds_read_b128 v[182:185], v159 offset:32768
	v_mfma_f32_32x32x16_bf16 v[32:47], v[210:213], v[186:189], v[32:47]
	ds_read_b128 v[186:189], v161
	v_mfma_f32_32x32x16_bf16 v[0:15], v[210:213], v[206:209], v[0:15]
	ds_read_b128 v[206:209], v161 offset:4096
	ds_read_b128 v[210:213], v159 offset:36864
	s_waitcnt vmcnt(6)
	s_barrier
	s_waitcnt lgkmcnt(0)
	v_mfma_f32_32x32x16_bf16 v[48:63], v[182:185], v[186:189], v[48:63]
	v_mfma_f32_32x32x16_bf16 v[16:31], v[182:185], v[206:209], v[16:31]
	ds_read_b128 v[182:185], v165
	v_mfma_f32_32x32x16_bf16 v[32:47], v[210:213], v[186:189], v[32:47]
	ds_read_b128 v[186:189], v156 offset:49152
	v_mfma_f32_32x32x16_bf16 v[0:15], v[210:213], v[206:209], v[0:15]
	ds_read_b128 v[206:209], v156 offset:53248
	ds_read_b128 v[210:213], v165 offset:4096
	s_waitcnt lgkmcnt(0)
	v_mfma_f32_32x32x16_bf16 v[48:63], v[182:185], v[186:189], v[48:63]
	v_lshl_add_u64 v[214:215], v[140:141], 0, s[42:43]
	s_mov_b32 m0, s41
	s_nop 0
	global_load_lds_dwordx4 v[214:215], off
	v_mfma_f32_32x32x16_bf16 v[16:31], v[182:185], v[206:209], v[16:31]
	s_mov_b64 s[42:43], 0x20180
	v_lshl_add_u64 v[182:183], v[140:141], 0, s[42:43]
	s_mov_b32 m0, s37
	s_nop 0
	global_load_lds_dwordx4 v[182:183], off
	v_mfma_f32_32x32x16_bf16 v[32:47], v[210:213], v[186:189], v[32:47]
	s_mov_b64 s[44:45], 0x40180
	v_lshl_add_u64 v[182:183], v[140:141], 0, s[44:45]
	s_mov_b32 m0, s31
	s_nop 0
	global_load_lds_dwordx4 v[182:183], off
	v_add_u32_e32 v182, v163, v221
	ds_read_b128 v[184:187], v182
	v_mfma_f32_32x32x16_bf16 v[0:15], v[210:213], v[206:209], v[0:15]
	ds_read_b128 v[206:209], v158 offset:49152
	ds_read_b128 v[210:213], v158 offset:53248
	ds_read_b128 v[214:217], v182 offset:4096
	s_waitcnt lgkmcnt(0)
	v_mfma_f32_32x32x16_bf16 v[48:63], v[184:187], v[206:209], v[48:63]
	s_mov_b64 s[44:45], 0x60180
	v_lshl_add_u64 v[188:189], v[140:141], 0, s[44:45]
	s_mov_b32 m0, s28
	s_nop 0
	global_load_lds_dwordx4 v[188:189], off
	v_mfma_f32_32x32x16_bf16 v[16:31], v[184:187], v[210:213], v[16:31]
	s_mov_b32 m0, s27
	s_nop 0
	global_load_lds_dwordx4 v[218:219], off
	v_mfma_f32_32x32x16_bf16 v[32:47], v[214:217], v[206:209], v[32:47]
	v_lshl_add_u64 v[184:185], v[138:139], 0, s[42:43]
	s_mov_b32 m0, s26
	s_nop 0
	global_load_lds_dwordx4 v[184:185], off
	v_add_u32_e32 v164, v163, v224
	ds_read_b128 v[184:187], v164
	ds_read_b128 v[206:209], v162 offset:49152
	v_mfma_f32_32x32x16_bf16 v[0:15], v[214:217], v[210:213], v[0:15]
	ds_read_b128 v[210:213], v162 offset:53248
	ds_read_b128 v[214:217], v164 offset:4096
	v_add_u32_e32 v163, v163, v225
	s_add_i32 s42, 0, 0x20000
	v_add_u32_e32 v226, s42, v181
	v_add_u32_e32 v181, v226, v220
	s_add_i32 s42, 0, 0x18000
	v_add_u32_e32 v227, s42, v222
	s_waitcnt lgkmcnt(0)
	v_mfma_f32_32x32x16_bf16 v[48:63], v[184:187], v[206:209], v[48:63]
	v_add_u32_e32 v183, v227, v220
	s_mov_b64 s[42:43], 0x200
	v_lshl_add_u64 v[188:189], v[138:139], 0, s[42:43]
	v_mfma_f32_32x32x16_bf16 v[16:31], v[184:187], v[210:213], v[16:31]
	ds_read_b128 v[184:187], v163
	v_mfma_f32_32x32x16_bf16 v[32:47], v[214:217], v[206:209], v[32:47]
	ds_read_b128 v[206:209], v161 offset:49152
	v_mfma_f32_32x32x16_bf16 v[0:15], v[214:217], v[210:213], v[0:15]
	ds_read_b128 v[210:213], v161 offset:53248
	ds_read_b128 v[214:217], v163 offset:4096
	s_waitcnt vmcnt(6)
	s_barrier
; #define MFMA(a, b, c) __builtin_amdgcn_mfma_f32_32x32x16_bf16((a), (b), (c), 0, 0, 0)
;     ...
;   for (int kt = 0; kt < nk; ++kt) {
;     if (DIST == 2 && kt + 1 < nk) {
;       if (NLD == 6) asm volatile("s_waitcnt vmcnt(6)" ::: "memory");
;       else if (NLD == 5) asm volatile("s_waitcnt vmcnt(5)" ::: "memory");
;       else asm volatile("s_waitcnt vmcnt(8)" ::: "memory");
;     } else {
;       asm volatile("s_waitcnt vmcnt(0)" ::: "memory");
;     }
;     __builtin_amdgcn_s_barrier();
;     const bool pre = (kt + DIST < nk);
;     const char* base = smem + (kt % NSTG) * STAGE;
;     const char* pa = base + (wrow_act + r) * 128;
;     const char* pw = base + ABYTES + (wrow_w + r) * 128;
;     constexpr int NM = NI * MJ;
;     constexpr int PPS = (NLD + 1) / 2;
; #pragma unroll
;     for (int s = 0; s < 4; ++s) {
;       bf16x8 af[MJ], wf[NI];
; #pragma unroll
;       for (int j = 0; j < MJ; ++j) af[j] = *(const bf16x8*)(pa + j * 32 * 128 + xo[s]);
; #pragma unroll
;       for (int i = 0; i < NI; ++i) wf[i] = *(const bf16x8*)(pw + i * 32 * 128 + xo[s]);
; #pragma unroll
;       for (int m = 0; m < NM; ++m) {
;         const int i = m / MJ, j = m % MJ;
;         acc[i][j] = MFMA(wf[i], af[j], acc[i][j]);
;         if (s < 2 && NM >= PPS) {
;           constexpr int EVERY = (NM / PPS) > 0 ? (NM / PPS) : 1;
;           if ((m + 1) % EVERY == 0) {
;             const int pc = s * PPS + (m + 1) / EVERY - 1;
;             if ((m + 1) / EVERY <= PPS && pc < NLD) {
;               __builtin_amdgcn_sched_barrier(0);
;               if (pre) issue_piece(kt + DIST, pc);
;               __builtin_amdgcn_sched_barrier(0);
;             }
;           }
;         }
;         if (s < 2 && NM < PPS) {
;           const int slot = s * NM + m;
;           __builtin_amdgcn_sched_barrier(0);
; #pragma unroll
;           for (int pc = 0; pc < NLD; ++pc)
;             if ((pc * 2 * NM) / NLD == slot && pre) issue_piece(kt + DIST, pc);
;           __builtin_amdgcn_sched_barrier(0);
;         }
;       }
;     }
;   }
	s_waitcnt lgkmcnt(0)
	v_mfma_f32_32x32x16_bf16 v[48:63], v[184:187], v[206:209], v[48:63]
	v_mfma_f32_32x32x16_bf16 v[16:31], v[184:187], v[210:213], v[16:31]
	ds_read_b128 v[184:187], v181
	v_mfma_f32_32x32x16_bf16 v[32:47], v[214:217], v[206:209], v[32:47]
	ds_read_b128 v[206:209], v183
	v_mfma_f32_32x32x16_bf16 v[0:15], v[214:217], v[210:213], v[0:15]
	ds_read_b128 v[210:213], v183 offset:4096
	ds_read_b128 v[214:217], v181 offset:4096
	s_waitcnt lgkmcnt(0)
	v_mfma_f32_32x32x16_bf16 v[48:63], v[184:187], v[206:209], v[48:63]
	v_lshl_add_u64 v[218:219], v[140:141], 0, s[42:43]
	s_mov_b32 m0, s25
	s_nop 0
	global_load_lds_dwordx4 v[218:219], off
	v_mfma_f32_32x32x16_bf16 v[16:31], v[184:187], v[210:213], v[16:31]
	s_mov_b64 s[42:43], 0x20200
	v_lshl_add_u64 v[184:185], v[140:141], 0, s[42:43]
	s_mov_b32 m0, s24
	s_nop 0
	global_load_lds_dwordx4 v[184:185], off
	v_mfma_f32_32x32x16_bf16 v[32:47], v[214:217], v[206:209], v[32:47]
	s_mov_b64 s[44:45], 0x40200
	v_lshl_add_u64 v[184:185], v[140:141], 0, s[44:45]
	s_mov_b32 m0, s23
	s_nop 0
	global_load_lds_dwordx4 v[184:185], off
	v_add_u32_e32 v184, v226, v221
	ds_read_b128 v[206:209], v184
	v_add_u32_e32 v186, v227, v221
	v_mfma_f32_32x32x16_bf16 v[0:15], v[214:217], v[210:213], v[0:15]
	ds_read_b128 v[210:213], v186
	ds_read_b128 v[214:217], v186 offset:4096
	ds_read_b128 v[218:221], v184 offset:4096
	s_waitcnt lgkmcnt(0)
	v_mfma_f32_32x32x16_bf16 v[48:63], v[206:209], v[210:213], v[48:63]
	s_mov_b64 s[44:45], 0x60200
	v_lshl_add_u64 v[222:223], v[140:141], 0, s[44:45]
	s_mov_b32 m0, s22
	s_nop 0
	global_load_lds_dwordx4 v[222:223], off
	v_mfma_f32_32x32x16_bf16 v[16:31], v[206:209], v[214:217], v[16:31]
	s_mov_b32 m0, s21
	s_nop 0
	global_load_lds_dwordx4 v[188:189], off
	v_mfma_f32_32x32x16_bf16 v[32:47], v[218:221], v[210:213], v[32:47]
	v_lshl_add_u64 v[188:189], v[138:139], 0, s[42:43]
	s_mov_b32 m0, s13
	s_nop 0
	global_load_lds_dwordx4 v[188:189], off
	v_add_u32_e32 v187, v226, v224
	ds_read_b128 v[206:209], v187
	v_add_u32_e32 v189, v227, v224
	ds_read_b128 v[210:213], v189
	v_mfma_f32_32x32x16_bf16 v[0:15], v[218:221], v[214:217], v[0:15]
	ds_read_b128 v[214:217], v189 offset:4096
	ds_read_b128 v[218:221], v187 offset:4096
	v_add_u32_e32 v185, v226, v225
	v_add_u32_e32 v188, v227, v225
	s_mov_b64 s[42:43], 0x280
	v_lshl_add_u64 v[222:223], v[138:139], 0, s[42:43]
	s_waitcnt lgkmcnt(0)
	v_mfma_f32_32x32x16_bf16 v[48:63], v[206:209], v[210:213], v[48:63]
	v_mfma_f32_32x32x16_bf16 v[16:31], v[206:209], v[214:217], v[16:31]
	ds_read_b128 v[206:209], v185
	v_mfma_f32_32x32x16_bf16 v[32:47], v[218:221], v[210:213], v[32:47]
	ds_read_b128 v[210:213], v188
	v_mfma_f32_32x32x16_bf16 v[0:15], v[218:221], v[214:217], v[0:15]
	ds_read_b128 v[214:217], v188 offset:4096
	ds_read_b128 v[218:221], v185 offset:4096
	s_waitcnt vmcnt(6)
	s_barrier
	s_waitcnt lgkmcnt(0)
	v_mfma_f32_32x32x16_bf16 v[48:63], v[206:209], v[210:213], v[48:63]
	v_mfma_f32_32x32x16_bf16 v[16:31], v[206:209], v[214:217], v[16:31]
	ds_read_b128 v[206:209], v155 offset:32768
	v_mfma_f32_32x32x16_bf16 v[32:47], v[218:221], v[210:213], v[32:47]
	ds_read_b128 v[210:213], v156
	v_mfma_f32_32x32x16_bf16 v[0:15], v[218:221], v[214:217], v[0:15]
	ds_read_b128 v[214:217], v156 offset:4096
	ds_read_b128 v[218:221], v155 offset:36864
	s_waitcnt lgkmcnt(0)
	v_mfma_f32_32x32x16_bf16 v[48:63], v[206:209], v[210:213], v[48:63]
	v_lshl_add_u64 v[224:225], v[140:141], 0, s[42:43]
	s_mov_b32 m0, s3
	s_nop 0
	global_load_lds_dwordx4 v[224:225], off
	v_mfma_f32_32x32x16_bf16 v[16:31], v[206:209], v[214:217], v[16:31]
	s_mov_b64 s[42:43], 0x20280
	v_lshl_add_u64 v[206:207], v[140:141], 0, s[42:43]
	s_mov_b32 m0, s12
	s_nop 0
	global_load_lds_dwordx4 v[206:207], off
	v_mfma_f32_32x32x16_bf16 v[32:47], v[218:221], v[210:213], v[32:47]
	s_mov_b64 s[44:45], 0x40280
	v_lshl_add_u64 v[206:207], v[140:141], 0, s[44:45]
	s_mov_b32 m0, s29
	s_nop 0
	global_load_lds_dwordx4 v[206:207], off
	ds_read_b128 v[206:209], v157 offset:32768
	ds_read_b128 v[210:213], v158
	v_mfma_f32_32x32x16_bf16 v[0:15], v[218:221], v[214:217], v[0:15]
	ds_read_b128 v[214:217], v158 offset:4096
	ds_read_b128 v[218:221], v157 offset:36864
	s_waitcnt lgkmcnt(0)
	v_mfma_f32_32x32x16_bf16 v[48:63], v[206:209], v[210:213], v[48:63]
	s_mov_b64 s[44:45], 0x60280
	v_lshl_add_u64 v[224:225], v[140:141], 0, s[44:45]
	s_mov_b32 m0, s30
	s_nop 0
	global_load_lds_dwordx4 v[224:225], off
	v_mfma_f32_32x32x16_bf16 v[16:31], v[206:209], v[214:217], v[16:31]
	s_mov_b32 m0, s36
	s_nop 0
	global_load_lds_dwordx4 v[222:223], off
	v_mfma_f32_32x32x16_bf16 v[32:47], v[218:221], v[210:213], v[32:47]
	v_lshl_add_u64 v[206:207], v[138:139], 0, s[42:43]
	s_mov_b32 m0, s40
	s_nop 0
	global_load_lds_dwordx4 v[206:207], off
	ds_read_b128 v[206:209], v160 offset:32768
	ds_read_b128 v[210:213], v162
	v_mfma_f32_32x32x16_bf16 v[0:15], v[218:221], v[214:217], v[0:15]
	ds_read_b128 v[214:217], v162 offset:4096
	ds_read_b128 v[218:221], v160 offset:36864
	s_mov_b64 s[42:43], 0x300
	v_lshl_add_u64 v[222:223], v[138:139], 0, s[42:43]
	s_waitcnt lgkmcnt(0)
	v_mfma_f32_32x32x16_bf16 v[48:63], v[206:209], v[210:213], v[48:63]
	v_mfma_f32_32x32x16_bf16 v[16:31], v[206:209], v[214:217], v[16:31]
	ds_read_b128 v[206:209], v159 offset:32768
	v_mfma_f32_32x32x16_bf16 v[32:47], v[218:221], v[210:213], v[32:47]
	ds_read_b128 v[210:213], v161
	v_mfma_f32_32x32x16_bf16 v[0:15], v[218:221], v[214:217], v[0:15]
	ds_read_b128 v[214:217], v161 offset:4096
	ds_read_b128 v[218:221], v159 offset:36864
	s_waitcnt vmcnt(6)
	s_barrier
; #define MFMA(a, b, c) __builtin_amdgcn_mfma_f32_32x32x16_bf16((a), (b), (c), 0, 0, 0)
;     ...
;   for (int kt = 0; kt < nk; ++kt) {
;     if (DIST == 2 && kt + 1 < nk) {
;       if (NLD == 6) asm volatile("s_waitcnt vmcnt(6)" ::: "memory");
;       else if (NLD == 5) asm volatile("s_waitcnt vmcnt(5)" ::: "memory");
;       else asm volatile("s_waitcnt vmcnt(8)" ::: "memory");
;     } else {
;       asm volatile("s_waitcnt vmcnt(0)" ::: "memory");
;     }
;     __builtin_amdgcn_s_barrier();
;     const bool pre = (kt + DIST < nk);
;     const char* base = smem + (kt % NSTG) * STAGE;
;     const char* pa = base + (wrow_act + r) * 128;
;     const char* pw = base + ABYTES + (wrow_w + r) * 128;
;     constexpr int NM = NI * MJ;
;     constexpr int PPS = (NLD + 1) / 2;
; #pragma unroll
;     for (int s = 0; s < 4; ++s) {
;       bf16x8 af[MJ], wf[NI];
; #pragma unroll
;       for (int j = 0; j < MJ; ++j) af[j] = *(const bf16x8*)(pa + j * 32 * 128 + xo[s]);
; #pragma unroll
;       for (int i = 0; i < NI; ++i) wf[i] = *(const bf16x8*)(pw + i * 32 * 128 + xo[s]);
; #pragma unroll
;       for (int m = 0; m < NM; ++m) {
;         const int i = m / MJ, j = m % MJ;
;         acc[i][j] = MFMA(wf[i], af[j], acc[i][j]);
;         if (s < 2 && NM >= PPS) {
;           constexpr int EVERY = (NM / PPS) > 0 ? (NM / PPS) : 1;
;           if ((m + 1) % EVERY == 0) {
;             const int pc = s * PPS + (m + 1) / EVERY - 1;
;             if ((m + 1) / EVERY <= PPS && pc < NLD) {
;               __builtin_amdgcn_sched_barrier(0);
;               if (pre) issue_piece(kt + DIST, pc);
;               __builtin_amdgcn_sched_barrier(0);
;             }
;           }
;         }
;         if (s < 2 && NM < PPS) {
;           const int slot = s * NM + m;
;           __builtin_amdgcn_sched_barrier(0);
; #pragma unroll
;           for (int pc = 0; pc < NLD; ++pc)
;             if ((pc * 2 * NM) / NLD == slot && pre) issue_piece(kt + DIST, pc);
;           __builtin_amdgcn_sched_barrier(0);
;         }
;       }
;     }
;   }
	s_waitcnt lgkmcnt(0)
	v_mfma_f32_32x32x16_bf16 v[48:63], v[206:209], v[210:213], v[48:63]
	v_mfma_f32_32x32x16_bf16 v[16:31], v[206:209], v[214:217], v[16:31]
	ds_read_b128 v[206:209], v165
	v_mfma_f32_32x32x16_bf16 v[32:47], v[218:221], v[210:213], v[32:47]
	ds_read_b128 v[210:213], v156 offset:49152
	v_mfma_f32_32x32x16_bf16 v[0:15], v[218:221], v[214:217], v[0:15]
	ds_read_b128 v[214:217], v156 offset:53248
	ds_read_b128 v[218:221], v165 offset:4096
	s_waitcnt lgkmcnt(0)
	v_mfma_f32_32x32x16_bf16 v[48:63], v[206:209], v[210:213], v[48:63]
	v_lshl_add_u64 v[224:225], v[140:141], 0, s[42:43]
	s_mov_b32 m0, s41
	s_nop 0
	global_load_lds_dwordx4 v[224:225], off
	v_mfma_f32_32x32x16_bf16 v[16:31], v[206:209], v[214:217], v[16:31]
	s_mov_b64 s[38:39], 0x20300
	v_lshl_add_u64 v[206:207], v[140:141], 0, s[38:39]
	s_mov_b32 m0, s37
	s_nop 0
	global_load_lds_dwordx4 v[206:207], off
	v_mfma_f32_32x32x16_bf16 v[32:47], v[218:221], v[210:213], v[32:47]
	v_lshl_add_u64 v[206:207], v[140:141], 0, s[86:87]
	s_mov_b32 m0, s31
	s_nop 0
	global_load_lds_dwordx4 v[206:207], off
	ds_read_b128 v[206:209], v182
	ds_read_b128 v[210:213], v158 offset:49152
	v_mfma_f32_32x32x16_bf16 v[0:15], v[218:221], v[214:217], v[0:15]
	ds_read_b128 v[214:217], v158 offset:53248
	ds_read_b128 v[218:221], v182 offset:4096
	s_waitcnt lgkmcnt(0)
	v_mfma_f32_32x32x16_bf16 v[48:63], v[206:209], v[210:213], v[48:63]
	v_lshl_add_u64 v[224:225], v[140:141], 0, s[88:89]
	s_mov_b32 m0, s28
	s_nop 0
	global_load_lds_dwordx4 v[224:225], off
	v_mfma_f32_32x32x16_bf16 v[16:31], v[206:209], v[214:217], v[16:31]
	s_mov_b32 m0, s27
	s_nop 0
	global_load_lds_dwordx4 v[222:223], off
	v_mfma_f32_32x32x16_bf16 v[32:47], v[218:221], v[210:213], v[32:47]
	v_lshl_add_u64 v[206:207], v[138:139], 0, s[38:39]
	s_mov_b32 m0, s26
	s_nop 0
	global_load_lds_dwordx4 v[206:207], off
	ds_read_b128 v[206:209], v164
	ds_read_b128 v[210:213], v162 offset:49152
	v_mfma_f32_32x32x16_bf16 v[0:15], v[218:221], v[214:217], v[0:15]
	ds_read_b128 v[214:217], v162 offset:53248
	ds_read_b128 v[218:221], v164 offset:4096
	s_mov_b64 s[26:27], 0x380
	v_lshl_add_u64 v[222:223], v[138:139], 0, s[26:27]
	s_waitcnt lgkmcnt(0)
	v_mfma_f32_32x32x16_bf16 v[48:63], v[206:209], v[210:213], v[48:63]
	v_mfma_f32_32x32x16_bf16 v[16:31], v[206:209], v[214:217], v[16:31]
	ds_read_b128 v[206:209], v163
	v_mfma_f32_32x32x16_bf16 v[32:47], v[218:221], v[210:213], v[32:47]
	ds_read_b128 v[210:213], v161 offset:49152
	v_mfma_f32_32x32x16_bf16 v[0:15], v[218:221], v[214:217], v[0:15]
	ds_read_b128 v[214:217], v161 offset:53248
	ds_read_b128 v[218:221], v163 offset:4096
	s_waitcnt vmcnt(6)
	s_barrier
	s_waitcnt lgkmcnt(0)
	v_mfma_f32_32x32x16_bf16 v[48:63], v[206:209], v[210:213], v[48:63]
	v_mfma_f32_32x32x16_bf16 v[16:31], v[206:209], v[214:217], v[16:31]
	ds_read_b128 v[206:209], v181
	v_mfma_f32_32x32x16_bf16 v[32:47], v[218:221], v[210:213], v[32:47]
	ds_read_b128 v[210:213], v183
	v_mfma_f32_32x32x16_bf16 v[0:15], v[218:221], v[214:217], v[0:15]
	ds_read_b128 v[214:217], v183 offset:4096
	ds_read_b128 v[218:221], v181 offset:4096
	s_waitcnt lgkmcnt(0)
	v_mfma_f32_32x32x16_bf16 v[48:63], v[206:209], v[210:213], v[48:63]
	v_lshl_add_u64 v[224:225], v[140:141], 0, s[26:27]
	s_mov_b32 m0, s25
	s_nop 0
	global_load_lds_dwordx4 v[224:225], off
	v_mfma_f32_32x32x16_bf16 v[16:31], v[206:209], v[214:217], v[16:31]
	s_mov_b64 s[26:27], 0x20380
	v_lshl_add_u64 v[206:207], v[140:141], 0, s[26:27]
	s_mov_b32 m0, s24
	s_nop 0
	global_load_lds_dwordx4 v[206:207], off
	v_mfma_f32_32x32x16_bf16 v[32:47], v[218:221], v[210:213], v[32:47]
	s_mov_b64 s[24:25], 0x40380
	v_lshl_add_u64 v[206:207], v[140:141], 0, s[24:25]
	s_mov_b32 m0, s23
	s_nop 0
	global_load_lds_dwordx4 v[206:207], off
	ds_read_b128 v[206:209], v184
	ds_read_b128 v[210:213], v186
	v_mfma_f32_32x32x16_bf16 v[0:15], v[218:221], v[214:217], v[0:15]
	ds_read_b128 v[214:217], v186 offset:4096
	ds_read_b128 v[218:221], v184 offset:4096
	s_waitcnt lgkmcnt(0)
	v_mfma_f32_32x32x16_bf16 v[48:63], v[206:209], v[210:213], v[48:63]
	s_mov_b64 s[24:25], 0x60380
	v_lshl_add_u64 v[224:225], v[140:141], 0, s[24:25]
	s_mov_b32 m0, s22
	s_nop 0
	global_load_lds_dwordx4 v[224:225], off
	v_mfma_f32_32x32x16_bf16 v[16:31], v[206:209], v[214:217], v[16:31]
	s_mov_b32 m0, s21
	s_nop 0
	global_load_lds_dwordx4 v[222:223], off
	v_mfma_f32_32x32x16_bf16 v[32:47], v[218:221], v[210:213], v[32:47]
	v_lshl_add_u64 v[206:207], v[138:139], 0, s[26:27]
	s_mov_b32 m0, s13
	s_nop 0
	global_load_lds_dwordx4 v[206:207], off
	ds_read_b128 v[206:209], v187
	ds_read_b128 v[210:213], v189
	v_mfma_f32_32x32x16_bf16 v[0:15], v[218:221], v[214:217], v[0:15]
	ds_read_b128 v[214:217], v189 offset:4096
	ds_read_b128 v[218:221], v187 offset:4096
	s_mov_b64 s[22:23], 0x400
	v_lshl_add_u64 v[222:223], v[138:139], 0, s[22:23]
	s_waitcnt lgkmcnt(0)
	v_mfma_f32_32x32x16_bf16 v[48:63], v[206:209], v[210:213], v[48:63]
	v_mfma_f32_32x32x16_bf16 v[16:31], v[206:209], v[214:217], v[16:31]
	ds_read_b128 v[206:209], v185
	v_mfma_f32_32x32x16_bf16 v[32:47], v[218:221], v[210:213], v[32:47]
	ds_read_b128 v[210:213], v188
	v_mfma_f32_32x32x16_bf16 v[0:15], v[218:221], v[214:217], v[0:15]
	ds_read_b128 v[214:217], v188 offset:4096
	ds_read_b128 v[218:221], v185 offset:4096
	s_waitcnt vmcnt(6)
	s_barrier
; #define MFMA(a, b, c) __builtin_amdgcn_mfma_f32_32x32x16_bf16((a), (b), (c), 0, 0, 0)
;     ...
;   for (int kt = 0; kt < nk; ++kt) {
;     if (DIST == 2 && kt + 1 < nk) {
;       if (NLD == 6) asm volatile("s_waitcnt vmcnt(6)" ::: "memory");
;       else if (NLD == 5) asm volatile("s_waitcnt vmcnt(5)" ::: "memory");
;       else asm volatile("s_waitcnt vmcnt(8)" ::: "memory");
;     } else {
;       asm volatile("s_waitcnt vmcnt(0)" ::: "memory");
;     }
;     __builtin_amdgcn_s_barrier();
;     const bool pre = (kt + DIST < nk);
;     const char* base = smem + (kt % NSTG) * STAGE;
;     const char* pa = base + (wrow_act + r) * 128;
;     const char* pw = base + ABYTES + (wrow_w + r) * 128;
;     constexpr int NM = NI * MJ;
;     constexpr int PPS = (NLD + 1) / 2;
; #pragma unroll
;     for (int s = 0; s < 4; ++s) {
;       bf16x8 af[MJ], wf[NI];
; #pragma unroll
;       for (int j = 0; j < MJ; ++j) af[j] = *(const bf16x8*)(pa + j * 32 * 128 + xo[s]);
; #pragma unroll
;       for (int i = 0; i < NI; ++i) wf[i] = *(const bf16x8*)(pw + i * 32 * 128 + xo[s]);
; #pragma unroll
;       for (int m = 0; m < NM; ++m) {
;         const int i = m / MJ, j = m % MJ;
;         acc[i][j] = MFMA(wf[i], af[j], acc[i][j]);
;         if (s < 2 && NM >= PPS) {
;           constexpr int EVERY = (NM / PPS) > 0 ? (NM / PPS) : 1;
;           if ((m + 1) % EVERY == 0) {
;             const int pc = s * PPS + (m + 1) / EVERY - 1;
;             if ((m + 1) / EVERY <= PPS && pc < NLD) {
;               __builtin_amdgcn_sched_barrier(0);
;               if (pre) issue_piece(kt + DIST, pc);
;               __builtin_amdgcn_sched_barrier(0);
;             }
;           }
;         }
;         if (s < 2 && NM < PPS) {
;           const int slot = s * NM + m;
;           __builtin_amdgcn_sched_barrier(0);
; #pragma unroll
;           for (int pc = 0; pc < NLD; ++pc)
;             if ((pc * 2 * NM) / NLD == slot && pre) issue_piece(kt + DIST, pc);
;           __builtin_amdgcn_sched_barrier(0);
;         }
;       }
;     }
;   }
	s_waitcnt lgkmcnt(0)
	v_mfma_f32_32x32x16_bf16 v[48:63], v[206:209], v[210:213], v[48:63]
	v_mfma_f32_32x32x16_bf16 v[16:31], v[206:209], v[214:217], v[16:31]
	ds_read_b128 v[206:209], v155 offset:32768
	v_mfma_f32_32x32x16_bf16 v[32:47], v[218:221], v[210:213], v[32:47]
	ds_read_b128 v[210:213], v156
	v_mfma_f32_32x32x16_bf16 v[0:15], v[218:221], v[214:217], v[0:15]
	ds_read_b128 v[214:217], v156 offset:4096
	ds_read_b128 v[218:221], v155 offset:36864
	s_waitcnt lgkmcnt(0)
	v_mfma_f32_32x32x16_bf16 v[48:63], v[206:209], v[210:213], v[48:63]
	v_lshl_add_u64 v[224:225], v[140:141], 0, s[22:23]
	s_mov_b32 m0, s3
	s_nop 0
	global_load_lds_dwordx4 v[224:225], off
	v_mfma_f32_32x32x16_bf16 v[16:31], v[206:209], v[214:217], v[16:31]
	s_mov_b64 s[22:23], 0x20400
	v_lshl_add_u64 v[206:207], v[140:141], 0, s[22:23]
	s_mov_b32 m0, s12
	s_nop 0
	global_load_lds_dwordx4 v[206:207], off
	v_mfma_f32_32x32x16_bf16 v[32:47], v[218:221], v[210:213], v[32:47]
	s_mov_b64 s[24:25], 0x40400
	v_lshl_add_u64 v[206:207], v[140:141], 0, s[24:25]
	s_mov_b32 m0, s29
	s_nop 0
	global_load_lds_dwordx4 v[206:207], off
	ds_read_b128 v[206:209], v157 offset:32768
	ds_read_b128 v[210:213], v158
	v_mfma_f32_32x32x16_bf16 v[0:15], v[218:221], v[214:217], v[0:15]
	ds_read_b128 v[214:217], v158 offset:4096
	ds_read_b128 v[218:221], v157 offset:36864
	s_waitcnt lgkmcnt(0)
	v_mfma_f32_32x32x16_bf16 v[48:63], v[206:209], v[210:213], v[48:63]
	s_mov_b64 s[24:25], 0x60400
	v_lshl_add_u64 v[224:225], v[140:141], 0, s[24:25]
	s_mov_b32 m0, s30
	s_nop 0
	global_load_lds_dwordx4 v[224:225], off
	v_mfma_f32_32x32x16_bf16 v[16:31], v[206:209], v[214:217], v[16:31]
	s_mov_b32 m0, s36
	s_nop 0
	global_load_lds_dwordx4 v[222:223], off
	v_mfma_f32_32x32x16_bf16 v[32:47], v[218:221], v[210:213], v[32:47]
	v_lshl_add_u64 v[206:207], v[138:139], 0, s[22:23]
	s_mov_b32 m0, s40
	s_nop 0
	global_load_lds_dwordx4 v[206:207], off
	ds_read_b128 v[206:209], v160 offset:32768
	ds_read_b128 v[210:213], v162
	v_mfma_f32_32x32x16_bf16 v[0:15], v[218:221], v[214:217], v[0:15]
	ds_read_b128 v[214:217], v162 offset:4096
	ds_read_b128 v[218:221], v160 offset:36864
	s_mov_b64 s[22:23], 0x480
	v_lshl_add_u64 v[222:223], v[138:139], 0, s[22:23]
	s_waitcnt lgkmcnt(0)
	v_mfma_f32_32x32x16_bf16 v[48:63], v[206:209], v[210:213], v[48:63]
	v_mfma_f32_32x32x16_bf16 v[16:31], v[206:209], v[214:217], v[16:31]
	ds_read_b128 v[206:209], v159 offset:32768
	v_mfma_f32_32x32x16_bf16 v[32:47], v[218:221], v[210:213], v[32:47]
	ds_read_b128 v[210:213], v161
	v_mfma_f32_32x32x16_bf16 v[0:15], v[218:221], v[214:217], v[0:15]
	ds_read_b128 v[214:217], v161 offset:4096
	ds_read_b128 v[218:221], v159 offset:36864
	s_waitcnt vmcnt(6)
	s_barrier
	s_waitcnt lgkmcnt(0)
	v_mfma_f32_32x32x16_bf16 v[48:63], v[206:209], v[210:213], v[48:63]
	v_mfma_f32_32x32x16_bf16 v[16:31], v[206:209], v[214:217], v[16:31]
	ds_read_b128 v[206:209], v165
	v_mfma_f32_32x32x16_bf16 v[32:47], v[218:221], v[210:213], v[32:47]
	ds_read_b128 v[210:213], v156 offset:49152
	v_mfma_f32_32x32x16_bf16 v[0:15], v[218:221], v[214:217], v[0:15]
	ds_read_b128 v[214:217], v156 offset:53248
	ds_read_b128 v[218:221], v165 offset:4096
	s_waitcnt lgkmcnt(0)
	v_mfma_f32_32x32x16_bf16 v[48:63], v[206:209], v[210:213], v[48:63]
	v_readfirstlane_b32 s3, v205
	v_lshl_add_u64 v[224:225], v[140:141], 0, s[22:23]
	s_mov_b32 m0, s3
	s_nop 0
	global_load_lds_dwordx4 v[224:225], off
	v_mfma_f32_32x32x16_bf16 v[16:31], v[206:209], v[214:217], v[16:31]
	s_mov_b64 s[26:27], 0x20480
	v_readfirstlane_b32 s12, v204
	v_lshl_add_u64 v[206:207], v[140:141], 0, s[26:27]
	s_mov_b32 m0, s12
	s_nop 0
	global_load_lds_dwordx4 v[206:207], off
	v_mfma_f32_32x32x16_bf16 v[32:47], v[218:221], v[210:213], v[32:47]
	s_mov_b64 s[22:23], 0x40480
	v_lshl_add_u64 v[204:205], v[140:141], 0, s[22:23]
	v_readfirstlane_b32 s22, v203
	s_mov_b32 m0, s22
	s_nop 0
	global_load_lds_dwordx4 v[204:205], off
	ds_read_b128 v[204:207], v182
	ds_read_b128 v[208:211], v158 offset:49152
	v_mfma_f32_32x32x16_bf16 v[0:15], v[218:221], v[214:217], v[0:15]
	ds_read_b128 v[212:215], v158 offset:53248
	ds_read_b128 v[216:219], v182 offset:4096
	s_waitcnt lgkmcnt(0)
	v_mfma_f32_32x32x16_bf16 v[48:63], v[204:207], v[208:211], v[48:63]
	s_mov_b64 s[24:25], 0x60480
	v_readfirstlane_b32 s23, v200
	v_lshl_add_u64 v[220:221], v[140:141], 0, s[24:25]
	s_mov_b32 m0, s23
	s_nop 0
	global_load_lds_dwordx4 v[220:221], off
	v_mfma_f32_32x32x16_bf16 v[16:31], v[204:207], v[212:215], v[16:31]
	v_readfirstlane_b32 s24, v195
	s_mov_b32 m0, s24
	s_nop 0
	global_load_lds_dwordx4 v[222:223], off
	v_mfma_f32_32x32x16_bf16 v[32:47], v[216:219], v[208:211], v[32:47]
	v_readfirstlane_b32 s25, v197
	v_lshl_add_u64 v[204:205], v[138:139], 0, s[26:27]
	s_mov_b32 m0, s25
	s_nop 0
	global_load_lds_dwordx4 v[204:205], off
	ds_read_b128 v[204:207], v164
	ds_read_b128 v[208:211], v162 offset:49152
	v_mfma_f32_32x32x16_bf16 v[0:15], v[216:219], v[212:215], v[0:15]
	ds_read_b128 v[212:215], v162 offset:53248
	ds_read_b128 v[216:219], v164 offset:4096
	s_mov_b64 s[26:27], 0x500
	v_lshl_add_u64 v[220:221], v[138:139], 0, s[26:27]
	s_waitcnt lgkmcnt(0)
	v_mfma_f32_32x32x16_bf16 v[48:63], v[204:207], v[208:211], v[48:63]
	v_mfma_f32_32x32x16_bf16 v[16:31], v[204:207], v[212:215], v[16:31]
	ds_read_b128 v[204:207], v163
	v_mfma_f32_32x32x16_bf16 v[32:47], v[216:219], v[208:211], v[32:47]
	ds_read_b128 v[208:211], v161 offset:49152
	v_mfma_f32_32x32x16_bf16 v[0:15], v[216:219], v[212:215], v[0:15]
	ds_read_b128 v[212:215], v161 offset:53248
	ds_read_b128 v[216:219], v163 offset:4096
	s_waitcnt vmcnt(6)
	s_barrier
; #define MFMA(a, b, c) __builtin_amdgcn_mfma_f32_32x32x16_bf16((a), (b), (c), 0, 0, 0)
;     ...
;   for (int kt = 0; kt < nk; ++kt) {
;     if (DIST == 2 && kt + 1 < nk) {
;       if (NLD == 6) asm volatile("s_waitcnt vmcnt(6)" ::: "memory");
;       else if (NLD == 5) asm volatile("s_waitcnt vmcnt(5)" ::: "memory");
;       else asm volatile("s_waitcnt vmcnt(8)" ::: "memory");
;     } else {
;       asm volatile("s_waitcnt vmcnt(0)" ::: "memory");
;     }
;     __builtin_amdgcn_s_barrier();
;     const bool pre = (kt + DIST < nk);
;     const char* base = smem + (kt % NSTG) * STAGE;
;     const char* pa = base + (wrow_act + r) * 128;
;     const char* pw = base + ABYTES + (wrow_w + r) * 128;
;     constexpr int NM = NI * MJ;
;     constexpr int PPS = (NLD + 1) / 2;
; #pragma unroll
;     for (int s = 0; s < 4; ++s) {
;       bf16x8 af[MJ], wf[NI];
; #pragma unroll
;       for (int j = 0; j < MJ; ++j) af[j] = *(const bf16x8*)(pa + j * 32 * 128 + xo[s]);
; #pragma unroll
;       for (int i = 0; i < NI; ++i) wf[i] = *(const bf16x8*)(pw + i * 32 * 128 + xo[s]);
; #pragma unroll
;       for (int m = 0; m < NM; ++m) {
;         const int i = m / MJ, j = m % MJ;
;         acc[i][j] = MFMA(wf[i], af[j], acc[i][j]);
;         if (s < 2 && NM >= PPS) {
;           constexpr int EVERY = (NM / PPS) > 0 ? (NM / PPS) : 1;
;           if ((m + 1) % EVERY == 0) {
;             const int pc = s * PPS + (m + 1) / EVERY - 1;
;             if ((m + 1) / EVERY <= PPS && pc < NLD) {
;               __builtin_amdgcn_sched_barrier(0);
;               if (pre) issue_piece(kt + DIST, pc);
;               __builtin_amdgcn_sched_barrier(0);
;             }
;           }
;         }
;         if (s < 2 && NM < PPS) {
;           const int slot = s * NM + m;
;           __builtin_amdgcn_sched_barrier(0);
; #pragma unroll
;           for (int pc = 0; pc < NLD; ++pc)
;             if ((pc * 2 * NM) / NLD == slot && pre) issue_piece(kt + DIST, pc);
;           __builtin_amdgcn_sched_barrier(0);
;         }
;       }
;     }
;   }
	s_waitcnt lgkmcnt(0)
	v_mfma_f32_32x32x16_bf16 v[48:63], v[204:207], v[208:211], v[48:63]
	v_mfma_f32_32x32x16_bf16 v[16:31], v[204:207], v[212:215], v[16:31]
	ds_read_b128 v[204:207], v181
	v_mfma_f32_32x32x16_bf16 v[32:47], v[216:219], v[208:211], v[32:47]
	ds_read_b128 v[208:211], v183
	v_mfma_f32_32x32x16_bf16 v[0:15], v[216:219], v[212:215], v[0:15]
	ds_read_b128 v[212:215], v183 offset:4096
	ds_read_b128 v[216:219], v181 offset:4096
	s_waitcnt lgkmcnt(0)
	v_mfma_f32_32x32x16_bf16 v[48:63], v[204:207], v[208:211], v[48:63]
	v_lshl_add_u64 v[222:223], v[140:141], 0, s[26:27]
	v_readfirstlane_b32 s26, v193
	s_mov_b32 m0, s26
	s_nop 0
	global_load_lds_dwordx4 v[222:223], off
	v_mfma_f32_32x32x16_bf16 v[16:31], v[204:207], v[212:215], v[16:31]
	s_mov_b64 s[30:31], 0x20500
	v_readfirstlane_b32 s27, v192
	v_lshl_add_u64 v[204:205], v[140:141], 0, s[30:31]
	s_mov_b32 m0, s27
	s_nop 0
	global_load_lds_dwordx4 v[204:205], off
	ds_read_b128 v[204:207], v184
	v_mfma_f32_32x32x16_bf16 v[32:47], v[216:219], v[208:211], v[32:47]
	ds_read_b128 v[208:211], v186
	s_mov_b64 s[28:29], 0x40500
	v_lshl_add_u64 v[192:193], v[140:141], 0, s[28:29]
	v_readfirstlane_b32 s28, v191
	s_mov_b32 m0, s28
	s_nop 0
	global_load_lds_dwordx4 v[192:193], off
	v_mfma_f32_32x32x16_bf16 v[0:15], v[216:219], v[212:215], v[0:15]
	ds_read_b128 v[212:215], v186 offset:4096
	ds_read_b128 v[216:219], v184 offset:4096
	s_waitcnt lgkmcnt(0)
	v_mfma_f32_32x32x16_bf16 v[48:63], v[204:207], v[208:211], v[48:63]
	s_mov_b64 s[36:37], 0x60500
	v_readfirstlane_b32 s29, v190
	v_lshl_add_u64 v[192:193], v[140:141], 0, s[36:37]
	s_mov_b32 m0, s29
	s_nop 0
	global_load_lds_dwordx4 v[192:193], off
	v_mfma_f32_32x32x16_bf16 v[16:31], v[204:207], v[212:215], v[16:31]
	s_mov_b32 m0, s21
	s_nop 0
	global_load_lds_dwordx4 v[220:221], off
	v_mfma_f32_32x32x16_bf16 v[32:47], v[216:219], v[208:211], v[32:47]
	v_lshl_add_u64 v[190:191], v[138:139], 0, s[30:31]
	s_mov_b32 m0, s13
	s_nop 0
	global_load_lds_dwordx4 v[190:191], off
	ds_read_b128 v[190:193], v187
	ds_read_b128 v[204:207], v189
	ds_read_b128 v[208:211], v189 offset:4096
	v_mfma_f32_32x32x16_bf16 v[0:15], v[216:219], v[212:215], v[0:15]
	ds_read_b128 v[212:215], v187 offset:4096
	s_mov_b64 s[30:31], 0x580
	v_lshl_add_u64 v[216:217], v[138:139], 0, s[30:31]
	s_waitcnt lgkmcnt(0)
	v_mfma_f32_32x32x16_bf16 v[48:63], v[190:193], v[204:207], v[48:63]
	v_mfma_f32_32x32x16_bf16 v[16:31], v[190:193], v[208:211], v[16:31]
	ds_read_b128 v[190:193], v185
	v_mfma_f32_32x32x16_bf16 v[32:47], v[212:215], v[204:207], v[32:47]
	ds_read_b128 v[204:207], v188
	v_mfma_f32_32x32x16_bf16 v[0:15], v[212:215], v[208:211], v[0:15]
	ds_read_b128 v[208:211], v188 offset:4096
	ds_read_b128 v[212:215], v185 offset:4096
	s_waitcnt vmcnt(6)
	s_barrier
	s_waitcnt lgkmcnt(0)
	v_mfma_f32_32x32x16_bf16 v[48:63], v[190:193], v[204:207], v[48:63]
	v_mfma_f32_32x32x16_bf16 v[16:31], v[190:193], v[208:211], v[16:31]
	ds_read_b128 v[190:193], v155 offset:32768
	v_mfma_f32_32x32x16_bf16 v[32:47], v[212:215], v[204:207], v[32:47]
	ds_read_b128 v[204:207], v156
	v_mfma_f32_32x32x16_bf16 v[0:15], v[212:215], v[208:211], v[0:15]
	ds_read_b128 v[208:211], v156 offset:4096
	ds_read_b128 v[212:215], v155 offset:36864
	s_waitcnt lgkmcnt(0)
	v_mfma_f32_32x32x16_bf16 v[48:63], v[190:193], v[204:207], v[48:63]
	v_lshl_add_u64 v[218:219], v[140:141], 0, s[30:31]
	v_readfirstlane_b32 s30, v196
	s_mov_b32 m0, s30
	s_nop 0
	global_load_lds_dwordx4 v[218:219], off
	v_mfma_f32_32x32x16_bf16 v[16:31], v[190:193], v[208:211], v[16:31]
	s_mov_b64 s[38:39], 0x20580
	v_readfirstlane_b32 s31, v198
	v_lshl_add_u64 v[190:191], v[140:141], 0, s[38:39]
	s_mov_b32 m0, s31
	s_nop 0
	global_load_lds_dwordx4 v[190:191], off
	v_mfma_f32_32x32x16_bf16 v[32:47], v[212:215], v[204:207], v[32:47]
	v_readfirstlane_b32 s36, v199
	v_lshl_add_u64 v[190:191], v[140:141], 0, s[90:91]
	s_mov_b32 m0, s36
	s_nop 0
	global_load_lds_dwordx4 v[190:191], off
	ds_read_b128 v[190:193], v157 offset:32768
	ds_read_b128 v[196:199], v158
	ds_read_b128 v[204:207], v158 offset:4096
	v_mfma_f32_32x32x16_bf16 v[0:15], v[212:215], v[208:211], v[0:15]
	ds_read_b128 v[208:211], v157 offset:36864
	s_waitcnt lgkmcnt(0)
	v_mfma_f32_32x32x16_bf16 v[48:63], v[190:193], v[196:199], v[48:63]
	v_readfirstlane_b32 s37, v201
	v_lshl_add_u64 v[212:213], v[140:141], 0, s[96:97]
	s_mov_b32 m0, s37
	s_nop 0
	global_load_lds_dwordx4 v[212:213], off
	v_mfma_f32_32x32x16_bf16 v[16:31], v[190:193], v[204:207], v[16:31]
	v_readfirstlane_b32 s40, v194
	s_mov_b32 m0, s40
	s_nop 0
	global_load_lds_dwordx4 v[216:217], off
	v_mfma_f32_32x32x16_bf16 v[32:47], v[208:211], v[196:199], v[32:47]
	v_readfirstlane_b32 s41, v202
	v_lshl_add_u64 v[190:191], v[138:139], 0, s[38:39]
	s_mov_b32 m0, s41
	s_nop 0
	global_load_lds_dwordx4 v[190:191], off
	ds_read_b128 v[190:193], v160 offset:32768
	ds_read_b128 v[194:197], v162
	ds_read_b128 v[198:201], v162 offset:4096
	v_mfma_f32_32x32x16_bf16 v[0:15], v[208:211], v[204:207], v[0:15]
	ds_read_b128 v[202:205], v160 offset:36864
	s_mov_b64 s[38:39], 0x600
	v_lshl_add_u64 v[206:207], v[138:139], 0, s[38:39]
	s_waitcnt lgkmcnt(0)
	v_mfma_f32_32x32x16_bf16 v[48:63], v[190:193], v[194:197], v[48:63]
	v_mfma_f32_32x32x16_bf16 v[16:31], v[190:193], v[198:201], v[16:31]
	ds_read_b128 v[190:193], v159 offset:32768
	v_mfma_f32_32x32x16_bf16 v[32:47], v[202:205], v[194:197], v[32:47]
	ds_read_b128 v[194:197], v161
	v_mfma_f32_32x32x16_bf16 v[0:15], v[202:205], v[198:201], v[0:15]
	ds_read_b128 v[198:201], v161 offset:4096
	ds_read_b128 v[202:205], v159 offset:36864
	s_waitcnt vmcnt(6)
	s_barrier
; #define MFMA(a, b, c) __builtin_amdgcn_mfma_f32_32x32x16_bf16((a), (b), (c), 0, 0, 0)
;     ...
;   for (int kt = 0; kt < nk; ++kt) {
;     if (DIST == 2 && kt + 1 < nk) {
;       if (NLD == 6) asm volatile("s_waitcnt vmcnt(6)" ::: "memory");
;       else if (NLD == 5) asm volatile("s_waitcnt vmcnt(5)" ::: "memory");
;       else asm volatile("s_waitcnt vmcnt(8)" ::: "memory");
;     } else {
;       asm volatile("s_waitcnt vmcnt(0)" ::: "memory");
;     }
;     __builtin_amdgcn_s_barrier();
;     const bool pre = (kt + DIST < nk);
;     const char* base = smem + (kt % NSTG) * STAGE;
;     const char* pa = base + (wrow_act + r) * 128;
;     const char* pw = base + ABYTES + (wrow_w + r) * 128;
;     constexpr int NM = NI * MJ;
;     constexpr int PPS = (NLD + 1) / 2;
; #pragma unroll
;     for (int s = 0; s < 4; ++s) {
;       bf16x8 af[MJ], wf[NI];
; #pragma unroll
;       for (int j = 0; j < MJ; ++j) af[j] = *(const bf16x8*)(pa + j * 32 * 128 + xo[s]);
; #pragma unroll
;       for (int i = 0; i < NI; ++i) wf[i] = *(const bf16x8*)(pw + i * 32 * 128 + xo[s]);
; #pragma unroll
;       for (int m = 0; m < NM; ++m) {
;         const int i = m / MJ, j = m % MJ;
;         acc[i][j] = MFMA(wf[i], af[j], acc[i][j]);
;         if (s < 2 && NM >= PPS) {
;           constexpr int EVERY = (NM / PPS) > 0 ? (NM / PPS) : 1;
;           if ((m + 1) % EVERY == 0) {
;             const int pc = s * PPS + (m + 1) / EVERY - 1;
;             if ((m + 1) / EVERY <= PPS && pc < NLD) {
;               __builtin_amdgcn_sched_barrier(0);
;               if (pre) issue_piece(kt + DIST, pc);
;               __builtin_amdgcn_sched_barrier(0);
;             }
;           }
;         }
;         if (s < 2 && NM < PPS) {
;           const int slot = s * NM + m;
;           __builtin_amdgcn_sched_barrier(0);
; #pragma unroll
;           for (int pc = 0; pc < NLD; ++pc)
;             if ((pc * 2 * NM) / NLD == slot && pre) issue_piece(kt + DIST, pc);
;           __builtin_amdgcn_sched_barrier(0);
;         }
;       }
;     }
;   }
	s_waitcnt lgkmcnt(0)
	v_mfma_f32_32x32x16_bf16 v[48:63], v[190:193], v[194:197], v[48:63]
	v_mfma_f32_32x32x16_bf16 v[16:31], v[190:193], v[198:201], v[16:31]
	ds_read_b128 v[190:193], v165
	v_mfma_f32_32x32x16_bf16 v[32:47], v[202:205], v[194:197], v[32:47]
	ds_read_b128 v[194:197], v156 offset:49152
	v_mfma_f32_32x32x16_bf16 v[0:15], v[202:205], v[198:201], v[0:15]
	ds_read_b128 v[198:201], v156 offset:53248
	ds_read_b128 v[202:205], v165 offset:4096
	s_waitcnt lgkmcnt(0)
	v_mfma_f32_32x32x16_bf16 v[48:63], v[190:193], v[194:197], v[48:63]
	v_lshl_add_u64 v[208:209], v[140:141], 0, s[38:39]
	s_mov_b32 m0, s3
	s_nop 0
	global_load_lds_dwordx4 v[208:209], off
	v_mfma_f32_32x32x16_bf16 v[16:31], v[190:193], v[198:201], v[16:31]
	s_mov_b64 s[38:39], 0x20600
	v_lshl_add_u64 v[190:191], v[140:141], 0, s[38:39]
	s_mov_b32 m0, s12
	s_nop 0
	global_load_lds_dwordx4 v[190:191], off
	v_mfma_f32_32x32x16_bf16 v[32:47], v[202:205], v[194:197], v[32:47]
	v_lshl_add_u64 v[190:191], v[140:141], 0, s[6:7]
	s_mov_b32 m0, s22
	s_nop 0
	global_load_lds_dwordx4 v[190:191], off
	ds_read_b128 v[190:193], v182
	ds_read_b128 v[194:197], v158 offset:49152
	v_mfma_f32_32x32x16_bf16 v[0:15], v[202:205], v[198:201], v[0:15]
	ds_read_b128 v[198:201], v158 offset:53248
	ds_read_b128 v[202:205], v182 offset:4096
	s_waitcnt lgkmcnt(0)
	v_mfma_f32_32x32x16_bf16 v[48:63], v[190:193], v[194:197], v[48:63]
	v_lshl_add_u64 v[208:209], v[140:141], 0, s[68:69]
	s_mov_b32 m0, s23
	s_nop 0
	global_load_lds_dwordx4 v[208:209], off
	v_mfma_f32_32x32x16_bf16 v[16:31], v[190:193], v[198:201], v[16:31]
	s_mov_b32 m0, s24
	s_nop 0
	global_load_lds_dwordx4 v[206:207], off
	v_mfma_f32_32x32x16_bf16 v[32:47], v[202:205], v[194:197], v[32:47]
	v_lshl_add_u64 v[190:191], v[138:139], 0, s[38:39]
	s_mov_b32 m0, s25
	s_nop 0
	global_load_lds_dwordx4 v[190:191], off
	ds_read_b128 v[190:193], v164
	ds_read_b128 v[194:197], v162 offset:49152
	v_mfma_f32_32x32x16_bf16 v[0:15], v[202:205], v[198:201], v[0:15]
	ds_read_b128 v[198:201], v162 offset:53248
	ds_read_b128 v[202:205], v164 offset:4096
	s_mov_b64 s[38:39], 0x680
	v_lshl_add_u64 v[206:207], v[138:139], 0, s[38:39]
	s_waitcnt lgkmcnt(0)
	v_mfma_f32_32x32x16_bf16 v[48:63], v[190:193], v[194:197], v[48:63]
	v_mfma_f32_32x32x16_bf16 v[16:31], v[190:193], v[198:201], v[16:31]
	ds_read_b128 v[190:193], v163
	v_mfma_f32_32x32x16_bf16 v[32:47], v[202:205], v[194:197], v[32:47]
	ds_read_b128 v[194:197], v161 offset:49152
	v_mfma_f32_32x32x16_bf16 v[0:15], v[202:205], v[198:201], v[0:15]
	ds_read_b128 v[198:201], v161 offset:53248
	ds_read_b128 v[202:205], v163 offset:4096
	s_waitcnt vmcnt(6)
	s_barrier
	s_waitcnt lgkmcnt(0)
	v_mfma_f32_32x32x16_bf16 v[48:63], v[190:193], v[194:197], v[48:63]
	v_mfma_f32_32x32x16_bf16 v[16:31], v[190:193], v[198:201], v[16:31]
	ds_read_b128 v[190:193], v181
	v_mfma_f32_32x32x16_bf16 v[32:47], v[202:205], v[194:197], v[32:47]
	ds_read_b128 v[194:197], v183
	v_mfma_f32_32x32x16_bf16 v[0:15], v[202:205], v[198:201], v[0:15]
	ds_read_b128 v[198:201], v183 offset:4096
	ds_read_b128 v[202:205], v181 offset:4096
	s_waitcnt lgkmcnt(0)
	v_mfma_f32_32x32x16_bf16 v[48:63], v[190:193], v[194:197], v[48:63]
	v_lshl_add_u64 v[208:209], v[140:141], 0, s[38:39]
	s_mov_b32 m0, s26
	s_nop 0
	global_load_lds_dwordx4 v[208:209], off
	v_mfma_f32_32x32x16_bf16 v[16:31], v[190:193], v[198:201], v[16:31]
	s_mov_b64 s[38:39], 0x20680
	v_lshl_add_u64 v[190:191], v[140:141], 0, s[38:39]
	s_mov_b32 m0, s27
	s_nop 0
	global_load_lds_dwordx4 v[190:191], off
	v_mfma_f32_32x32x16_bf16 v[32:47], v[202:205], v[194:197], v[32:47]
	v_lshl_add_u64 v[190:191], v[140:141], 0, s[58:59]
	s_mov_b32 m0, s28
	s_nop 0
	global_load_lds_dwordx4 v[190:191], off
	ds_read_b128 v[190:193], v184
	ds_read_b128 v[194:197], v186
	v_mfma_f32_32x32x16_bf16 v[0:15], v[202:205], v[198:201], v[0:15]
	ds_read_b128 v[198:201], v186 offset:4096
	ds_read_b128 v[202:205], v184 offset:4096
	s_waitcnt lgkmcnt(0)
	v_mfma_f32_32x32x16_bf16 v[48:63], v[190:193], v[194:197], v[48:63]
	v_lshl_add_u64 v[208:209], v[140:141], 0, s[60:61]
	s_mov_b32 m0, s29
	s_nop 0
	global_load_lds_dwordx4 v[208:209], off
	v_mfma_f32_32x32x16_bf16 v[16:31], v[190:193], v[198:201], v[16:31]
	s_mov_b32 m0, s21
	s_nop 0
	global_load_lds_dwordx4 v[206:207], off
	v_mfma_f32_32x32x16_bf16 v[32:47], v[202:205], v[194:197], v[32:47]
	v_lshl_add_u64 v[190:191], v[138:139], 0, s[38:39]
	s_mov_b32 m0, s13
	s_nop 0
	global_load_lds_dwordx4 v[190:191], off
	ds_read_b128 v[190:193], v187
	ds_read_b128 v[194:197], v189
	v_mfma_f32_32x32x16_bf16 v[0:15], v[202:205], v[198:201], v[0:15]
	ds_read_b128 v[198:201], v189 offset:4096
	ds_read_b128 v[202:205], v187 offset:4096
	s_mov_b64 s[26:27], 0x700
	v_lshl_add_u64 v[206:207], v[138:139], 0, s[26:27]
	s_waitcnt lgkmcnt(0)
	v_mfma_f32_32x32x16_bf16 v[48:63], v[190:193], v[194:197], v[48:63]
	v_mfma_f32_32x32x16_bf16 v[16:31], v[190:193], v[198:201], v[16:31]
	ds_read_b128 v[190:193], v185
	v_mfma_f32_32x32x16_bf16 v[32:47], v[202:205], v[194:197], v[32:47]
	ds_read_b128 v[194:197], v188
	v_mfma_f32_32x32x16_bf16 v[0:15], v[202:205], v[198:201], v[0:15]
	ds_read_b128 v[198:201], v188 offset:4096
	ds_read_b128 v[202:205], v185 offset:4096
	s_waitcnt vmcnt(6)
	s_barrier
; #define MFMA(a, b, c) __builtin_amdgcn_mfma_f32_32x32x16_bf16((a), (b), (c), 0, 0, 0)
;     ...
;   for (int kt = 0; kt < nk; ++kt) {
;     if (DIST == 2 && kt + 1 < nk) {
;       if (NLD == 6) asm volatile("s_waitcnt vmcnt(6)" ::: "memory");
;       else if (NLD == 5) asm volatile("s_waitcnt vmcnt(5)" ::: "memory");
;       else asm volatile("s_waitcnt vmcnt(8)" ::: "memory");
;     } else {
;       asm volatile("s_waitcnt vmcnt(0)" ::: "memory");
;     }
;     __builtin_amdgcn_s_barrier();
;     const bool pre = (kt + DIST < nk);
;     const char* base = smem + (kt % NSTG) * STAGE;
;     const char* pa = base + (wrow_act + r) * 128;
;     const char* pw = base + ABYTES + (wrow_w + r) * 128;
;     constexpr int NM = NI * MJ;
;     constexpr int PPS = (NLD + 1) / 2;
; #pragma unroll
;     for (int s = 0; s < 4; ++s) {
;       bf16x8 af[MJ], wf[NI];
; #pragma unroll
;       for (int j = 0; j < MJ; ++j) af[j] = *(const bf16x8*)(pa + j * 32 * 128 + xo[s]);
; #pragma unroll
;       for (int i = 0; i < NI; ++i) wf[i] = *(const bf16x8*)(pw + i * 32 * 128 + xo[s]);
; #pragma unroll
;       for (int m = 0; m < NM; ++m) {
;         const int i = m / MJ, j = m % MJ;
;         acc[i][j] = MFMA(wf[i], af[j], acc[i][j]);
;         if (s < 2 && NM >= PPS) {
;           constexpr int EVERY = (NM / PPS) > 0 ? (NM / PPS) : 1;
;           if ((m + 1) % EVERY == 0) {
;             const int pc = s * PPS + (m + 1) / EVERY - 1;
;             if ((m + 1) / EVERY <= PPS && pc < NLD) {
;               __builtin_amdgcn_sched_barrier(0);
;               if (pre) issue_piece(kt + DIST, pc);
;               __builtin_amdgcn_sched_barrier(0);
;             }
;           }
;         }
;         if (s < 2 && NM < PPS) {
;           const int slot = s * NM + m;
;           __builtin_amdgcn_sched_barrier(0);
; #pragma unroll
;           for (int pc = 0; pc < NLD; ++pc)
;             if ((pc * 2 * NM) / NLD == slot && pre) issue_piece(kt + DIST, pc);
;           __builtin_amdgcn_sched_barrier(0);
;         }
;       }
;     }
;   }
	s_waitcnt lgkmcnt(0)
	v_mfma_f32_32x32x16_bf16 v[48:63], v[190:193], v[194:197], v[48:63]
	v_mfma_f32_32x32x16_bf16 v[16:31], v[190:193], v[198:201], v[16:31]
	ds_read_b128 v[190:193], v155 offset:32768
	v_mfma_f32_32x32x16_bf16 v[32:47], v[202:205], v[194:197], v[32:47]
	ds_read_b128 v[194:197], v156
	v_mfma_f32_32x32x16_bf16 v[0:15], v[202:205], v[198:201], v[0:15]
	ds_read_b128 v[198:201], v156 offset:4096
	ds_read_b128 v[202:205], v155 offset:36864
	s_waitcnt lgkmcnt(0)
	v_mfma_f32_32x32x16_bf16 v[48:63], v[190:193], v[194:197], v[48:63]
	v_lshl_add_u64 v[208:209], v[140:141], 0, s[26:27]
	s_mov_b32 m0, s30
	s_nop 0
	global_load_lds_dwordx4 v[208:209], off
	v_mfma_f32_32x32x16_bf16 v[16:31], v[190:193], v[198:201], v[16:31]
	s_mov_b64 s[26:27], 0x20700
	v_lshl_add_u64 v[190:191], v[140:141], 0, s[26:27]
	s_mov_b32 m0, s31
	s_nop 0
	global_load_lds_dwordx4 v[190:191], off
	v_mfma_f32_32x32x16_bf16 v[32:47], v[202:205], v[194:197], v[32:47]
	s_mov_b64 s[28:29], 0x40700
	v_lshl_add_u64 v[190:191], v[140:141], 0, s[28:29]
	s_mov_b32 m0, s36
	s_nop 0
	global_load_lds_dwordx4 v[190:191], off
	ds_read_b128 v[190:193], v157 offset:32768
	ds_read_b128 v[194:197], v158
	v_mfma_f32_32x32x16_bf16 v[0:15], v[202:205], v[198:201], v[0:15]
	ds_read_b128 v[198:201], v158 offset:4096
	ds_read_b128 v[202:205], v157 offset:36864
	s_waitcnt lgkmcnt(0)
	v_mfma_f32_32x32x16_bf16 v[48:63], v[190:193], v[194:197], v[48:63]
	s_mov_b64 s[28:29], 0x60700
	v_lshl_add_u64 v[208:209], v[140:141], 0, s[28:29]
	s_mov_b32 m0, s37
	s_nop 0
	global_load_lds_dwordx4 v[208:209], off
	v_mfma_f32_32x32x16_bf16 v[16:31], v[190:193], v[198:201], v[16:31]
	s_mov_b32 m0, s40
	s_nop 0
	global_load_lds_dwordx4 v[206:207], off
	v_mfma_f32_32x32x16_bf16 v[32:47], v[202:205], v[194:197], v[32:47]
	v_lshl_add_u64 v[190:191], v[138:139], 0, s[26:27]
	s_mov_b32 m0, s41
	s_nop 0
	global_load_lds_dwordx4 v[190:191], off
	ds_read_b128 v[190:193], v160 offset:32768
	ds_read_b128 v[194:197], v162
	v_mfma_f32_32x32x16_bf16 v[0:15], v[202:205], v[198:201], v[0:15]
	ds_read_b128 v[198:201], v162 offset:4096
	ds_read_b128 v[202:205], v160 offset:36864
	s_mov_b64 s[26:27], 0x780
	v_lshl_add_u64 v[206:207], v[138:139], 0, s[26:27]
	s_waitcnt lgkmcnt(0)
	v_mfma_f32_32x32x16_bf16 v[48:63], v[190:193], v[194:197], v[48:63]
	v_mfma_f32_32x32x16_bf16 v[16:31], v[190:193], v[198:201], v[16:31]
	ds_read_b128 v[190:193], v159 offset:32768
	v_mfma_f32_32x32x16_bf16 v[32:47], v[202:205], v[194:197], v[32:47]
	ds_read_b128 v[194:197], v161
	v_mfma_f32_32x32x16_bf16 v[0:15], v[202:205], v[198:201], v[0:15]
	ds_read_b128 v[198:201], v161 offset:4096
	ds_read_b128 v[202:205], v159 offset:36864
	s_waitcnt vmcnt(6)
	s_barrier
	s_waitcnt lgkmcnt(0)
	v_mfma_f32_32x32x16_bf16 v[48:63], v[190:193], v[194:197], v[48:63]
	v_mfma_f32_32x32x16_bf16 v[16:31], v[190:193], v[198:201], v[16:31]
	ds_read_b128 v[190:193], v165
	v_mfma_f32_32x32x16_bf16 v[32:47], v[202:205], v[194:197], v[32:47]
	ds_read_b128 v[194:197], v156 offset:49152
	v_mfma_f32_32x32x16_bf16 v[0:15], v[202:205], v[198:201], v[0:15]
	ds_read_b128 v[198:201], v156 offset:53248
	ds_read_b128 v[202:205], v165 offset:4096
	s_waitcnt lgkmcnt(0)
	v_mfma_f32_32x32x16_bf16 v[48:63], v[190:193], v[194:197], v[48:63]
	v_lshl_add_u64 v[208:209], v[140:141], 0, s[26:27]
	s_mov_b32 m0, s3
	s_nop 0
	global_load_lds_dwordx4 v[208:209], off
	v_mfma_f32_32x32x16_bf16 v[16:31], v[190:193], v[198:201], v[16:31]
	s_mov_b64 s[26:27], 0x20780
	v_lshl_add_u64 v[190:191], v[140:141], 0, s[26:27]
	s_mov_b32 m0, s12
	s_nop 0
	global_load_lds_dwordx4 v[190:191], off
	v_mfma_f32_32x32x16_bf16 v[32:47], v[202:205], v[194:197], v[32:47]
	s_mov_b64 s[12:13], 0x40780
	v_lshl_add_u64 v[190:191], v[140:141], 0, s[12:13]
	s_mov_b32 m0, s22
	s_nop 0
	global_load_lds_dwordx4 v[190:191], off
	ds_read_b128 v[190:193], v182
	ds_read_b128 v[194:197], v158 offset:49152
	v_mfma_f32_32x32x16_bf16 v[0:15], v[202:205], v[198:201], v[0:15]
	ds_read_b128 v[198:201], v158 offset:53248
	ds_read_b128 v[202:205], v182 offset:4096
	s_waitcnt lgkmcnt(0)
	v_mfma_f32_32x32x16_bf16 v[48:63], v[190:193], v[194:197], v[48:63]
	s_mov_b64 s[12:13], 0x60780
	v_lshl_add_u64 v[140:141], v[140:141], 0, s[12:13]
	s_mov_b32 m0, s23
	s_nop 0
	global_load_lds_dwordx4 v[140:141], off
	v_mfma_f32_32x32x16_bf16 v[16:31], v[190:193], v[198:201], v[16:31]
	s_mov_b32 m0, s24
	s_nop 0
	global_load_lds_dwordx4 v[206:207], off
	v_mfma_f32_32x32x16_bf16 v[32:47], v[202:205], v[194:197], v[32:47]
	v_lshl_add_u64 v[138:139], v[138:139], 0, s[26:27]
	s_mov_b32 m0, s25
	s_nop 0
	global_load_lds_dwordx4 v[138:139], off
	ds_read_b128 v[138:141], v164
	ds_read_b128 v[190:193], v162 offset:49152
	ds_read_b128 v[194:197], v162 offset:53248
	v_mfma_f32_32x32x16_bf16 v[0:15], v[202:205], v[198:201], v[0:15]
	s_waitcnt lgkmcnt(0)
	v_mfma_f32_32x32x16_bf16 v[48:63], v[138:141], v[190:193], v[48:63]
	v_mfma_f32_32x32x16_bf16 v[16:31], v[138:141], v[194:197], v[16:31]
	ds_read_b128 v[138:141], v164 offset:4096
	s_waitcnt lgkmcnt(0)
	v_mfma_f32_32x32x16_bf16 v[32:47], v[138:141], v[190:193], v[32:47]
	v_mfma_f32_32x32x16_bf16 v[0:15], v[138:141], v[194:197], v[0:15]
	ds_read_b128 v[138:141], v163
	ds_read_b128 v[190:193], v161 offset:49152
	ds_read_b128 v[194:197], v161 offset:53248
	s_waitcnt lgkmcnt(0)
	v_mfma_f32_32x32x16_bf16 v[48:63], v[138:141], v[190:193], v[48:63]
	v_mfma_f32_32x32x16_bf16 v[16:31], v[138:141], v[194:197], v[16:31]
	ds_read_b128 v[138:141], v163 offset:4096
	s_waitcnt vmcnt(6)
	s_barrier
;     ...
;   for (int kt = 0; kt < nk; ++kt) {
;     if (DIST == 2 && kt + 1 < nk) {
;       if (NLD == 6) asm volatile("s_waitcnt vmcnt(6)" ::: "memory");
;       else if (NLD == 5) asm volatile("s_waitcnt vmcnt(5)" ::: "memory");
;       else asm volatile("s_waitcnt vmcnt(8)" ::: "memory");
;     } else {
;       asm volatile("s_waitcnt vmcnt(0)" ::: "memory");
;     }
;     __builtin_amdgcn_s_barrier();
;     const bool pre = (kt + DIST < nk);
;     const char* base = smem + (kt % NSTG) * STAGE;
;     const char* pa = base + (wrow_act + r) * 128;
;     const char* pw = base + ABYTES + (wrow_w + r) * 128;
;     constexpr int NM = NI * MJ;
;     constexpr int PPS = (NLD + 1) / 2;
; #pragma unroll
;     for (int s = 0; s < 4; ++s) {
;       bf16x8 af[MJ], wf[NI];
; #pragma unroll
;       for (int j = 0; j < MJ; ++j) af[j] = *(const bf16x8*)(pa + j * 32 * 128 + xo[s]);
; #pragma unroll
;       for (int i = 0; i < NI; ++i) wf[i] = *(const bf16x8*)(pw + i * 32 * 128 + xo[s]);
; #pragma unroll
;       for (int m = 0; m < NM; ++m) {
;         const int i = m / MJ, j = m % MJ;
;         acc[i][j] = MFMA(wf[i], af[j], acc[i][j]);
;         if (s < 2 && NM >= PPS) {
;           constexpr int EVERY = (NM / PPS) > 0 ? (NM / PPS) : 1;
;           if ((m + 1) % EVERY == 0) {
;             const int pc = s * PPS + (m + 1) / EVERY - 1;
;             if ((m + 1) / EVERY <= PPS && pc < NLD) {
;               __builtin_amdgcn_sched_barrier(0);
;               if (pre) issue_piece(kt + DIST, pc);
;               __builtin_amdgcn_sched_barrier(0);
;             }
;           }
;         }
;         if (s < 2 && NM < PPS) {
;           const int slot = s * NM + m;
;           __builtin_amdgcn_sched_barrier(0);
; #pragma unroll
;           for (int pc = 0; pc < NLD; ++pc)
;             if ((pc * 2 * NM) / NLD == slot && pre) issue_piece(kt + DIST, pc);
;           __builtin_amdgcn_sched_barrier(0);
;         }
;       }
;     }
;   }
;   __builtin_amdgcn_s_barrier();
; DEV void phase_outproj(const Params& p, int l, int hf, char* smem) {
;     ...
; #pragma unroll
;     for (int j = 0; j < 2; ++j) {
;       const int m = mt * 256 + wm * 64 + 32 * j + r;
;       const int bl = m / TP, tp = m - bl * TP;
;       const int b = hf * 2 + bl;
;       const int n0 = nt * 128 + wn * 64;
;       const float* src;
;       float* dst;
;       const float* gate;
;       if (tp < CTXL) {
	s_waitcnt lgkmcnt(0)
	v_mfma_f32_32x32x16_bf16 v[32:47], v[138:141], v[190:193], v[32:47]
	v_mfma_f32_32x32x16_bf16 v[0:15], v[138:141], v[194:197], v[0:15]
	ds_read_b128 v[138:141], v181
	ds_read_b128 v[190:193], v183
	ds_read_b128 v[194:197], v183 offset:4096
	ds_read_b128 v[198:201], v181 offset:4096
	s_waitcnt lgkmcnt(0)
	v_mfma_f32_32x32x16_bf16 v[48:63], v[138:141], v[190:193], v[48:63]
	v_mfma_f32_32x32x16_bf16 v[16:31], v[138:141], v[194:197], v[16:31]
	ds_read_b128 v[138:141], v184
	v_mfma_f32_32x32x16_bf16 v[32:47], v[198:201], v[190:193], v[32:47]
	ds_read_b128 v[190:193], v186
	v_mfma_f32_32x32x16_bf16 v[0:15], v[198:201], v[194:197], v[0:15]
	ds_read_b128 v[194:197], v186 offset:4096
	ds_read_b128 v[198:201], v184 offset:4096
	s_waitcnt lgkmcnt(0)
	v_mfma_f32_32x32x16_bf16 v[48:63], v[138:141], v[190:193], v[48:63]
	v_mfma_f32_32x32x16_bf16 v[16:31], v[138:141], v[194:197], v[16:31]
	ds_read_b128 v[138:141], v187
	v_mfma_f32_32x32x16_bf16 v[32:47], v[198:201], v[190:193], v[32:47]
	ds_read_b128 v[190:193], v189
	v_mfma_f32_32x32x16_bf16 v[0:15], v[198:201], v[194:197], v[0:15]
	ds_read_b128 v[194:197], v189 offset:4096
	s_waitcnt lgkmcnt(0)
	v_mfma_f32_32x32x16_bf16 v[48:63], v[138:141], v[190:193], v[48:63]
	v_mfma_f32_32x32x16_bf16 v[16:31], v[138:141], v[194:197], v[16:31]
	ds_read_b128 v[138:141], v187 offset:4096
	s_waitcnt lgkmcnt(0)
	v_mfma_f32_32x32x16_bf16 v[32:47], v[138:141], v[190:193], v[32:47]
	v_mfma_f32_32x32x16_bf16 v[0:15], v[138:141], v[194:197], v[0:15]
	ds_read_b128 v[138:141], v185
	ds_read_b128 v[190:193], v188
	ds_read_b128 v[186:189], v188 offset:4096
	s_waitcnt lgkmcnt(0)
	v_mfma_f32_32x32x16_bf16 v[48:63], v[138:141], v[190:193], v[48:63]
	v_mfma_f32_32x32x16_bf16 v[16:31], v[138:141], v[186:189], v[16:31]
	ds_read_b128 v[138:141], v185 offset:4096
	s_waitcnt vmcnt(0)
	s_barrier
	s_waitcnt lgkmcnt(0)
	v_mfma_f32_32x32x16_bf16 v[32:47], v[138:141], v[190:193], v[32:47]
	v_mfma_f32_32x32x16_bf16 v[0:15], v[138:141], v[186:189], v[0:15]
	ds_read_b128 v[138:141], v155 offset:32768
	ds_read_b128 v[182:185], v156
	ds_read_b128 v[186:189], v156 offset:4096
	ds_read_b128 v[190:193], v155 offset:36864
	s_waitcnt lgkmcnt(0)
	v_mfma_f32_32x32x16_bf16 v[48:63], v[138:141], v[182:185], v[48:63]
	v_mfma_f32_32x32x16_bf16 v[16:31], v[138:141], v[186:189], v[16:31]
	ds_read_b128 v[138:141], v157 offset:32768
	v_mfma_f32_32x32x16_bf16 v[32:47], v[190:193], v[182:185], v[32:47]
	ds_read_b128 v[182:185], v158
	v_mfma_f32_32x32x16_bf16 v[0:15], v[190:193], v[186:189], v[0:15]
	ds_read_b128 v[186:189], v158 offset:4096
	ds_read_b128 v[190:193], v157 offset:36864
	s_waitcnt lgkmcnt(0)
	v_mfma_f32_32x32x16_bf16 v[48:63], v[138:141], v[182:185], v[48:63]
	v_mfma_f32_32x32x16_bf16 v[16:31], v[138:141], v[186:189], v[16:31]
	ds_read_b128 v[138:141], v160 offset:32768
	v_mfma_f32_32x32x16_bf16 v[32:47], v[190:193], v[182:185], v[32:47]
	ds_read_b128 v[182:185], v162
	ds_read_b128 v[162:165], v162 offset:4096
	v_mfma_f32_32x32x16_bf16 v[0:15], v[190:193], v[186:189], v[0:15]
	s_waitcnt lgkmcnt(0)
	v_mfma_f32_32x32x16_bf16 v[48:63], v[138:141], v[182:185], v[48:63]
	v_mfma_f32_32x32x16_bf16 v[16:31], v[138:141], v[162:165], v[16:31]
	ds_read_b128 v[138:141], v160 offset:36864
	s_waitcnt lgkmcnt(0)
	v_mfma_f32_32x32x16_bf16 v[32:47], v[138:141], v[182:185], v[32:47]
	v_mfma_f32_32x32x16_bf16 v[0:15], v[138:141], v[162:165], v[0:15]
	ds_read_b128 v[138:141], v159 offset:32768
	ds_read_b128 v[162:165], v161
	ds_read_b128 v[182:185], v161 offset:4096
	ds_read_b128 v[156:159], v159 offset:36864
	s_barrier
	s_waitcnt lgkmcnt(0)
	v_mfma_f32_32x32x16_bf16 v[48:63], v[138:141], v[162:165], v[48:63]
	v_mfma_f32_32x32x16_bf16 v[16:31], v[138:141], v[182:185], v[16:31]
	v_mfma_f32_32x32x16_bf16 v[32:47], v[156:159], v[162:165], v[32:47]
	v_mfma_f32_32x32x16_bf16 v[0:15], v[156:159], v[182:185], v[0:15]
	s_and_saveexec_b64 s[12:13], vcc
	s_xor_b64 s[12:13], exec, s[12:13]
	s_cbranch_execz .LBB0_21
	v_lshlrev_b64 v[136:137], 25, v[134:135]
	v_readlane_b32 s24, v242, 1
	v_mul_i32_i24_e32 v134, 0xc00, v134
	v_readlane_b32 s28, v242, 5
	v_readlane_b32 s29, v242, 6
	v_ashrrev_i32_e32 v135, 31, v134
	v_lshlrev_b64 v[138:139], 12, v[144:145]
	v_lshl_add_u64 v[136:137], s[28:29], 0, v[136:137]
	v_lshl_add_u64 v[134:135], v[134:135], 2, s[0:1]
	s_mov_b64 s[22:23], 0x2000
	v_readlane_b32 s25, v242, 2
	v_readlane_b32 s26, v242, 3
	v_readlane_b32 s27, v242, 4
	v_readlane_b32 s30, v242, 7
	v_readlane_b32 s31, v242, 8
	v_lshl_add_u64 v[138:139], v[136:137], 0, v[138:139]
	v_lshl_add_u64 v[140:141], v[134:135], 0, s[22:23]

; #define MFMA(a, b, c) __builtin_amdgcn_mfma_f32_32x32x16_bf16((a), (b), (c), 0, 0, 0)
;     ...
;   const int tid = opaque_tid(), lane = tid & 63, h = lane >> 5, r = lane & 31;
;   const int nk = K >> 6;
;   const int cch = (tid & 7) ^ ((tid >> 4) & 7);
;   const u16* ga = A + (size_t)(tid >> 3) * lda + cch * 8;
;   const u16* gb = Bt + (size_t)(tid >> 3) * ldb + cch * 8;
;   char* lds_t = smem + tid * 16;
;   auto issue_piece = [&](int kt, int pc) {
;     char* st = lds_t + (kt % NSTG) * STAGE;
;     if (pc < 4)
;       __builtin_amdgcn_global_load_lds((const unsigned*)(ga + (size_t)(64 * pc) * lda + (size_t)kt * ksa), (unsigned __attribute__((address_space(3)))*)(st + pc * 8192), 16, 0, 0);
;     else
;       __builtin_amdgcn_global_load_lds((const unsigned*)(gb + (size_t)(64 * (pc - 4)) * ldb + (size_t)kt * ksb), (unsigned __attribute__((address_space(3)))*)(st + ABYTES + (pc - 4) * 8192), 16, 0, 0);
;   };
;   const int x = (r >> 1) & 7;
;   int xo[4];
; #pragma unroll
;   for (int s = 0; s < 4; ++s) xo[s] = (((2 * s + h) ^ x) << 4);
;   asm volatile("s_waitcnt vmcnt(0)" ::: "memory");
; #pragma unroll
;   for (int d = 0; d < DIST; ++d)
; #pragma unroll
;     for (int pc = 0; pc < NLD; ++pc) issue_piece(d, pc);
;   pre();
;   for (int kt = 0; kt < nk; ++kt) {
;     if (DIST == 2 && kt + 1 < nk) {
;       if (NLD == 6) asm volatile("s_waitcnt vmcnt(6)" ::: "memory");
;       else if (NLD == 5) asm volatile("s_waitcnt vmcnt(5)" ::: "memory");
;       else asm volatile("s_waitcnt vmcnt(8)" ::: "memory");
;     } else {
;       asm volatile("s_waitcnt vmcnt(0)" ::: "memory");
;     }
;     __builtin_amdgcn_s_barrier();
;     const bool pre = (kt + DIST < nk);
;     const char* base = smem + (kt % NSTG) * STAGE;
;     const char* pa = base + (wrow_act + r) * 128;
;     const char* pw = base + ABYTES + (wrow_w + r) * 128;
;     constexpr int NM = NI * MJ;
;     constexpr int PPS = (NLD + 1) / 2;
; #pragma unroll
;     for (int s = 0; s < 4; ++s) {
;       bf16x8 af[MJ], wf[NI];
; #pragma unroll
;       for (int j = 0; j < MJ; ++j) af[j] = *(const bf16x8*)(pa + j * 32 * 128 + xo[s]);
; #pragma unroll
;       for (int i = 0; i < NI; ++i) wf[i] = *(const bf16x8*)(pw + i * 32 * 128 + xo[s]);
; #pragma unroll
;       for (int m = 0; m < NM; ++m) {
;         const int i = m / MJ, j = m % MJ;
;         acc[i][j] = MFMA(wf[i], af[j], acc[i][j]);
.LBB0_31:
	s_ashr_i32 s6, s3, 4
	s_mul_i32 s8, s6, 33
	s_ashr_i32 s9, s8, 31
	s_and_b32 s5, s3, 15
	s_lshl_b64 s[8:9], s[8:9], 19
	v_mov_b32_e32 v4, v147
	s_add_u32 s8, s14, s8
	s_addc_u32 s9, s15, s9
	v_lshrrev_b32_e32 v0, 4, v4
	s_lshl_b32 s7, s5, 17
	v_xor_b32_e32 v5, v0, v4
	v_ashrrev_i32_e32 v0, 3, v4
	s_add_u32 s10, s16, s7
	v_ashrrev_i32_e32 v1, 31, v0
	s_addc_u32 s11, s17, 0
	v_lshlrev_b64 v[0:1], 11, v[0:1]
	v_lshlrev_b32_e32 v5, 4, v5
	v_lshl_add_u32 v70, v4, 4, 0
	v_lshl_add_u64 v[2:3], s[10:11], 0, v[0:1]
	v_lshl_add_u64 v[0:1], s[8:9], 0, v[0:1]
	v_and_b32_e32 v144, 0x70, v5
	v_readfirstlane_b32 s25, v70
	v_add_u32_e32 v71, 0x2000, v70
	v_lshl_add_u64 v[32:33], v[0:1], 0, v[144:145]
	s_waitcnt vmcnt(0)
	s_mov_b32 m0, s25
	v_readfirstlane_b32 s24, v71
	v_add_u32_e32 v69, 0x4000, v70
	global_load_lds_dwordx4 v[32:33], off
	v_lshl_add_u64 v[0:1], v[32:33], 0, s[56:57]
	s_mov_b32 m0, s24
	v_readfirstlane_b32 s23, v69
	v_add_u32_e32 v68, 0x6000, v70
	global_load_lds_dwordx4 v[0:1], off
	v_lshl_add_u64 v[0:1], v[32:33], 0, s[82:83]
	s_mov_b32 m0, s23
	v_readfirstlane_b32 s22, v68
	v_add_u32_e32 v65, 0x8000, v70
	global_load_lds_dwordx4 v[0:1], off
	v_lshl_add_u64 v[0:1], v[32:33], 0, s[92:93]
	s_mov_b32 m0, s22
	v_readfirstlane_b32 s21, v65
	v_add_u32_e32 v56, 0xc000, v70
	v_lshl_add_u64 v[34:35], v[2:3], 0, v[144:145]
	global_load_lds_dwordx4 v[0:1], off
	s_mov_b32 m0, s21
	v_readfirstlane_b32 s20, v56
	v_add_u32_e32 v59, 0xe000, v70
	global_load_lds_dwordx4 v[34:35], off
	v_lshl_add_u64 v[0:1], v[32:33], 0, s[62:63]
	s_mov_b32 m0, s20
	v_readfirstlane_b32 s19, v59
	v_add_u32_e32 v57, 0x10000, v70
	global_load_lds_dwordx4 v[0:1], off
	v_lshl_add_u64 v[0:1], v[32:33], 0, s[64:65]
	s_mov_b32 m0, s19
	v_readfirstlane_b32 s18, v57
	v_add_u32_e32 v50, 0x12000, v70
	global_load_lds_dwordx4 v[0:1], off
	v_lshl_add_u64 v[0:1], v[32:33], 0, s[66:67]
	s_mov_b32 m0, s18
	v_readfirstlane_b32 s13, v50
	v_add_u32_e32 v49, 0x14000, v70
	global_load_lds_dwordx4 v[0:1], off
	v_lshl_add_u64 v[0:1], v[32:33], 0, s[76:77]
	s_mov_b32 m0, s13
	v_readfirstlane_b32 s12, v49
	v_lshl_add_u64 v[2:3], v[34:35], 0, s[62:63]
	global_load_lds_dwordx4 v[0:1], off
	s_mov_b32 m0, s12
	v_lshrrev_b32_e32 v0, 5, v4
	global_load_lds_dwordx4 v[2:3], off
	v_bfe_u32 v2, v4, 1, 3
	v_bfe_u32 v1, v4, 5, 1
	v_bitop3_b32 v0, v0, v2, 1 bitop3:0x6c
	v_lshlrev_b32_e32 v64, 4, v0
	v_bitop3_b32 v0, v1, v2, 2 bitop3:0x36
	v_lshlrev_b32_e32 v86, 4, v0
	v_bitop3_b32 v0, v1, v2, 4 bitop3:0x36
	v_lshlrev_b32_e32 v87, 4, v0
	v_and_b32_e32 v0, 31, v4
	v_or_b32_e32 v4, v0, v52
	v_or_b32_e32 v0, v0, v53
	v_lshlrev_b32_e32 v84, 7, v0
	v_add_u32_e32 v51, 0, v84
	v_add_u32_e32 v36, v51, v64
	v_bitop3_b32 v8, v1, v2, 6 bitop3:0x36
	s_waitcnt vmcnt(5)
	s_barrier
	ds_read_b128 v[0:3], v36 offset:32768
	v_lshlrev_b32_e32 v85, 7, v4
	v_add_u32_e32 v58, 0, v85
	v_add_u32_e32 v37, v58, v64
	ds_read_b128 v[4:7], v37
	v_lshlrev_b32_e32 v88, 4, v8
	ds_read_b128 v[8:11], v37 offset:4096
	v_lshl_add_u64 v[66:67], v[34:35], 0, s[78:79]
	v_add_u32_e32 v44, 0x18000, v70
	s_waitcnt lgkmcnt(0)
	v_mfma_f32_32x32x16_bf16 v[16:31], v[0:3], v[4:7], 0
	v_add_u32_e32 v45, 0x1a000, v70
	v_readfirstlane_b32 s9, v44
	v_lshl_add_u64 v[4:5], v[32:33], 0, s[78:79]
	s_mov_b32 m0, s9
	v_readfirstlane_b32 s7, v45
	v_lshl_add_u64 v[6:7], v[32:33], 0, s[94:95]
	global_load_lds_dwordx4 v[4:5], off
	s_mov_b32 m0, s7
	s_nop 0
	global_load_lds_dwordx4 v[6:7], off
	v_mfma_f32_32x32x16_bf16 v[0:15], v[0:3], v[8:11], 0
	v_add_u32_e32 v46, 0x1c000, v70
	s_mov_b64 s[10:11], 0x40100
	v_readfirstlane_b32 s8, v46
	v_lshl_add_u64 v[38:39], v[32:33], 0, s[10:11]
	s_mov_b32 m0, s8
	s_nop 0
	global_load_lds_dwordx4 v[38:39], off
	v_add_u32_e32 v39, v51, v86
	ds_read_b128 v[40:43], v39 offset:32768
	v_add_u32_e32 v38, v58, v86
	ds_read_b128 v[60:63], v38
	ds_read_b128 v[72:75], v38 offset:4096
	s_waitcnt lgkmcnt(0)
	v_mfma_f32_32x32x16_bf16 v[16:31], v[40:43], v[60:63], v[16:31]
	v_add_u32_e32 v47, 0x1e000, v70
	s_mov_b64 s[10:11], 0x60100
	v_lshl_add_u64 v[60:61], v[32:33], 0, s[10:11]
	v_readfirstlane_b32 s10, v47
	s_mov_b32 m0, s10
	s_nop 0
	global_load_lds_dwordx4 v[60:61], off
	v_mfma_f32_32x32x16_bf16 v[0:15], v[40:43], v[72:75], v[0:15]
	v_add_u32_e32 v48, 0x20000, v70
	s_nop 0
	v_readfirstlane_b32 s11, v48
	s_mov_b32 m0, s11
	s_nop 0
	global_load_lds_dwordx4 v[66:67], off
	v_add_u32_e32 v40, v58, v87
	v_add_u32_e32 v41, v51, v87
	ds_read_b128 v[60:63], v40
	ds_read_b128 v[72:75], v40 offset:4096
	ds_read_b128 v[76:79], v41 offset:32768
	v_add_u32_e32 v42, v51, v88
	v_add_u32_e32 v43, v58, v88
	s_add_i32 s26, 0, 0x14000
	v_add_u32_e32 v89, s26, v84
	v_add_u32_e32 v51, v89, v64
	v_lshl_add_u64 v[66:67], v[34:35], 0, s[42:43]
	s_waitcnt lgkmcnt(0)
	v_mfma_f32_32x32x16_bf16 v[16:31], v[76:79], v[60:63], v[16:31]
	ds_read_b128 v[60:63], v42 offset:32768
	v_mfma_f32_32x32x16_bf16 v[0:15], v[76:79], v[72:75], v[0:15]
	ds_read_b128 v[72:75], v43 offset:4096
	ds_read_b128 v[76:79], v43
	s_waitcnt vmcnt(5)
	s_barrier
; #define MFMA(a, b, c) __builtin_amdgcn_mfma_f32_32x32x16_bf16((a), (b), (c), 0, 0, 0)
;     ...
;   for (int kt = 0; kt < nk; ++kt) {
;     if (DIST == 2 && kt + 1 < nk) {
;       if (NLD == 6) asm volatile("s_waitcnt vmcnt(6)" ::: "memory");
;       else if (NLD == 5) asm volatile("s_waitcnt vmcnt(5)" ::: "memory");
;       else asm volatile("s_waitcnt vmcnt(8)" ::: "memory");
;     } else {
;       asm volatile("s_waitcnt vmcnt(0)" ::: "memory");
;     }
;     __builtin_amdgcn_s_barrier();
;     const bool pre = (kt + DIST < nk);
;     const char* base = smem + (kt % NSTG) * STAGE;
;     const char* pa = base + (wrow_act + r) * 128;
;     const char* pw = base + ABYTES + (wrow_w + r) * 128;
;     constexpr int NM = NI * MJ;
;     constexpr int PPS = (NLD + 1) / 2;
; #pragma unroll
;     for (int s = 0; s < 4; ++s) {
;       bf16x8 af[MJ], wf[NI];
; #pragma unroll
;       for (int j = 0; j < MJ; ++j) af[j] = *(const bf16x8*)(pa + j * 32 * 128 + xo[s]);
; #pragma unroll
;       for (int i = 0; i < NI; ++i) wf[i] = *(const bf16x8*)(pw + i * 32 * 128 + xo[s]);
; #pragma unroll
;       for (int m = 0; m < NM; ++m) {
;         const int i = m / MJ, j = m % MJ;
;         acc[i][j] = MFMA(wf[i], af[j], acc[i][j]);
;         if (s < 2 && NM >= PPS) {
;           constexpr int EVERY = (NM / PPS) > 0 ? (NM / PPS) : 1;
;           if ((m + 1) % EVERY == 0) {
;             const int pc = s * PPS + (m + 1) / EVERY - 1;
;             if ((m + 1) / EVERY <= PPS && pc < NLD) {
;               __builtin_amdgcn_sched_barrier(0);
;               if (pre) issue_piece(kt + DIST, pc);
;               __builtin_amdgcn_sched_barrier(0);
;             }
;           }
;         }
;         if (s < 2 && NM < PPS) {
;           const int slot = s * NM + m;
;           __builtin_amdgcn_sched_barrier(0);
; #pragma unroll
;           for (int pc = 0; pc < NLD; ++pc)
;             if ((pc * 2 * NM) / NLD == slot && pre) issue_piece(kt + DIST, pc);
;           __builtin_amdgcn_sched_barrier(0);
;         }
;       }
;     }
;   }
	s_waitcnt lgkmcnt(0)
	v_mfma_f32_32x32x16_bf16 v[16:31], v[60:63], v[76:79], v[16:31]
	v_mfma_f32_32x32x16_bf16 v[0:15], v[60:63], v[72:75], v[0:15]
	ds_read_b128 v[60:63], v37 offset:49152
	ds_read_b128 v[72:75], v37 offset:53248
	ds_read_b128 v[76:79], v51
	s_waitcnt lgkmcnt(0)
	v_mfma_f32_32x32x16_bf16 v[16:31], v[76:79], v[60:63], v[16:31]
	s_mov_b32 m0, s25
	v_lshl_add_u64 v[60:61], v[32:33], 0, s[42:43]
	s_mov_b64 s[26:27], 0x20180
	v_lshl_add_u64 v[62:63], v[32:33], 0, s[26:27]
	global_load_lds_dwordx4 v[60:61], off
	s_mov_b32 m0, s24
	s_nop 0
	global_load_lds_dwordx4 v[62:63], off
	v_mfma_f32_32x32x16_bf16 v[0:15], v[76:79], v[72:75], v[0:15]
	s_mov_b64 s[26:27], 0x40180
	v_lshl_add_u64 v[60:61], v[32:33], 0, s[26:27]
	s_mov_b32 m0, s23
	s_nop 0
	global_load_lds_dwordx4 v[60:61], off
	v_add_u32_e32 v58, v89, v86
	ds_read_b128 v[60:63], v58
	ds_read_b128 v[72:75], v38 offset:49152
	ds_read_b128 v[76:79], v38 offset:53248
	s_waitcnt lgkmcnt(0)
	v_mfma_f32_32x32x16_bf16 v[16:31], v[60:63], v[72:75], v[16:31]
	s_mov_b64 s[26:27], 0x60180
	v_lshl_add_u64 v[72:73], v[32:33], 0, s[26:27]
	s_mov_b32 m0, s22
	s_nop 0
	global_load_lds_dwordx4 v[72:73], off
	ds_read_b128 v[72:75], v40 offset:49152
	v_mfma_f32_32x32x16_bf16 v[0:15], v[60:63], v[76:79], v[0:15]
	s_mov_b32 m0, s21
	s_nop 0
	global_load_lds_dwordx4 v[66:67], off
	v_add_u32_e32 v60, v89, v87
	ds_read_b128 v[76:79], v40 offset:53248
	ds_read_b128 v[80:83], v60
	v_add_u32_e32 v61, v89, v88
	s_add_i32 s26, 0, 0x18000
	v_add_u32_e32 v89, s26, v85
	s_add_i32 s26, 0, 0x20000
	v_add_u32_e32 v90, s26, v84
	v_add_u32_e32 v62, v89, v64
	v_add_u32_e32 v63, v90, v64
	s_waitcnt lgkmcnt(0)
	v_mfma_f32_32x32x16_bf16 v[16:31], v[80:83], v[72:75], v[16:31]
	ds_read_b128 v[72:75], v61
	v_lshl_add_u64 v[84:85], v[34:35], 0, s[52:53]
	v_mfma_f32_32x32x16_bf16 v[0:15], v[80:83], v[76:79], v[0:15]
	ds_read_b128 v[76:79], v43 offset:53248
	ds_read_b128 v[80:83], v43 offset:49152
	s_waitcnt vmcnt(5)
	s_barrier
	s_waitcnt lgkmcnt(0)
	v_mfma_f32_32x32x16_bf16 v[16:31], v[72:75], v[80:83], v[16:31]
	v_mfma_f32_32x32x16_bf16 v[0:15], v[72:75], v[76:79], v[0:15]
	ds_read_b128 v[72:75], v62
	ds_read_b128 v[76:79], v62 offset:4096
	ds_read_b128 v[80:83], v63
	s_waitcnt lgkmcnt(0)
	v_mfma_f32_32x32x16_bf16 v[16:31], v[80:83], v[72:75], v[16:31]
	s_mov_b32 m0, s20
	v_lshl_add_u64 v[66:67], v[32:33], 0, s[52:53]
	s_mov_b64 s[26:27], 0x20200
	v_lshl_add_u64 v[72:73], v[32:33], 0, s[26:27]
	global_load_lds_dwordx4 v[66:67], off
	s_mov_b32 m0, s19
	s_nop 0
	global_load_lds_dwordx4 v[72:73], off
	v_mfma_f32_32x32x16_bf16 v[0:15], v[80:83], v[76:79], v[0:15]
	s_mov_b64 s[26:27], 0x40200
	v_lshl_add_u64 v[66:67], v[32:33], 0, s[26:27]
	s_mov_b32 m0, s18
	s_nop 0
	global_load_lds_dwordx4 v[66:67], off
	v_add_u32_e32 v67, v90, v86
	ds_read_b128 v[72:75], v67
	v_add_u32_e32 v66, v89, v86
	ds_read_b128 v[76:79], v66
	ds_read_b128 v[80:83], v66 offset:4096
	s_waitcnt lgkmcnt(0)
	v_mfma_f32_32x32x16_bf16 v[16:31], v[72:75], v[76:79], v[16:31]
	s_mov_b64 s[26:27], 0x60200
	v_lshl_add_u64 v[76:77], v[32:33], 0, s[26:27]
	s_mov_b32 m0, s13
	s_nop 0
	global_load_lds_dwordx4 v[76:77], off
	v_mfma_f32_32x32x16_bf16 v[0:15], v[72:75], v[80:83], v[0:15]
	s_mov_b32 m0, s12
	s_nop 0
	global_load_lds_dwordx4 v[84:85], off
	v_add_u32_e32 v64, v89, v87
	v_add_u32_e32 v72, v90, v87
	ds_read_b128 v[74:77], v64
	ds_read_b128 v[78:81], v64 offset:4096
	ds_read_b128 v[82:85], v72
	v_add_u32_e32 v73, v89, v88
	s_waitcnt lgkmcnt(0)
	v_mfma_f32_32x32x16_bf16 v[16:31], v[82:85], v[74:77], v[16:31]
	v_add_u32_e32 v74, v90, v88
	v_lshl_add_u64 v[88:89], v[34:35], 0, s[88:89]
	v_mfma_f32_32x32x16_bf16 v[0:15], v[82:85], v[78:81], v[0:15]
	ds_read_b128 v[76:79], v74
	ds_read_b128 v[80:83], v73 offset:4096
	ds_read_b128 v[84:87], v73
	s_waitcnt vmcnt(5)
	s_barrier
	s_waitcnt lgkmcnt(0)
	v_mfma_f32_32x32x16_bf16 v[16:31], v[76:79], v[84:87], v[16:31]
	v_mfma_f32_32x32x16_bf16 v[0:15], v[76:79], v[80:83], v[0:15]
	ds_read_b128 v[76:79], v37
	ds_read_b128 v[80:83], v37 offset:4096
	ds_read_b128 v[84:87], v36 offset:32768
	s_waitcnt lgkmcnt(0)
	v_mfma_f32_32x32x16_bf16 v[16:31], v[84:87], v[76:79], v[16:31]
	s_mov_b32 m0, s9
	v_lshl_add_u64 v[76:77], v[32:33], 0, s[88:89]
	s_mov_b64 s[26:27], 0x20280
	v_lshl_add_u64 v[78:79], v[32:33], 0, s[26:27]
	global_load_lds_dwordx4 v[76:77], off
	s_mov_b32 m0, s7
	s_nop 0
	global_load_lds_dwordx4 v[78:79], off
	v_mfma_f32_32x32x16_bf16 v[0:15], v[84:87], v[80:83], v[0:15]
	s_mov_b64 s[26:27], 0x40280
	v_lshl_add_u64 v[76:77], v[32:33], 0, s[26:27]
	s_mov_b32 m0, s8
	s_nop 0
	global_load_lds_dwordx4 v[76:77], off
	ds_read_b128 v[76:79], v39 offset:32768
	ds_read_b128 v[80:83], v38
	ds_read_b128 v[84:87], v38 offset:4096
	s_waitcnt lgkmcnt(0)
	v_mfma_f32_32x32x16_bf16 v[16:31], v[76:79], v[80:83], v[16:31]
	s_mov_b64 s[26:27], 0x60280
	v_lshl_add_u64 v[80:81], v[32:33], 0, s[26:27]
	s_mov_b32 m0, s10
	s_nop 0
	global_load_lds_dwordx4 v[80:81], off
	v_mfma_f32_32x32x16_bf16 v[0:15], v[76:79], v[84:87], v[0:15]
	s_mov_b32 m0, s11
	s_nop 0
	global_load_lds_dwordx4 v[88:89], off
	ds_read_b128 v[76:79], v40
	ds_read_b128 v[80:83], v40 offset:4096
	ds_read_b128 v[84:87], v41 offset:32768
	v_lshl_add_u64 v[88:89], v[34:35], 0, s[70:71]
	s_waitcnt lgkmcnt(0)
	v_mfma_f32_32x32x16_bf16 v[16:31], v[84:87], v[76:79], v[16:31]
	ds_read_b128 v[76:79], v42 offset:32768
	v_mfma_f32_32x32x16_bf16 v[0:15], v[84:87], v[80:83], v[0:15]
	ds_read_b128 v[80:83], v43 offset:4096
	ds_read_b128 v[84:87], v43
	s_waitcnt vmcnt(5)
	s_barrier
; #define MFMA(a, b, c) __builtin_amdgcn_mfma_f32_32x32x16_bf16((a), (b), (c), 0, 0, 0)
;     ...
;   for (int kt = 0; kt < nk; ++kt) {
;     if (DIST == 2 && kt + 1 < nk) {
;       if (NLD == 6) asm volatile("s_waitcnt vmcnt(6)" ::: "memory");
;       else if (NLD == 5) asm volatile("s_waitcnt vmcnt(5)" ::: "memory");
;       else asm volatile("s_waitcnt vmcnt(8)" ::: "memory");
;     } else {
;       asm volatile("s_waitcnt vmcnt(0)" ::: "memory");
;     }
;     __builtin_amdgcn_s_barrier();
;     const bool pre = (kt + DIST < nk);
;     const char* base = smem + (kt % NSTG) * STAGE;
;     const char* pa = base + (wrow_act + r) * 128;
;     const char* pw = base + ABYTES + (wrow_w + r) * 128;
;     constexpr int NM = NI * MJ;
;     constexpr int PPS = (NLD + 1) / 2;
; #pragma unroll
;     for (int s = 0; s < 4; ++s) {
;       bf16x8 af[MJ], wf[NI];
; #pragma unroll
;       for (int j = 0; j < MJ; ++j) af[j] = *(const bf16x8*)(pa + j * 32 * 128 + xo[s]);
; #pragma unroll
;       for (int i = 0; i < NI; ++i) wf[i] = *(const bf16x8*)(pw + i * 32 * 128 + xo[s]);
; #pragma unroll
;       for (int m = 0; m < NM; ++m) {
;         const int i = m / MJ, j = m % MJ;
;         acc[i][j] = MFMA(wf[i], af[j], acc[i][j]);
;         if (s < 2 && NM >= PPS) {
;           constexpr int EVERY = (NM / PPS) > 0 ? (NM / PPS) : 1;
;           if ((m + 1) % EVERY == 0) {
;             const int pc = s * PPS + (m + 1) / EVERY - 1;
;             if ((m + 1) / EVERY <= PPS && pc < NLD) {
;               __builtin_amdgcn_sched_barrier(0);
;               if (pre) issue_piece(kt + DIST, pc);
;               __builtin_amdgcn_sched_barrier(0);
;             }
;           }
;         }
;         if (s < 2 && NM < PPS) {
;           const int slot = s * NM + m;
;           __builtin_amdgcn_sched_barrier(0);
; #pragma unroll
;           for (int pc = 0; pc < NLD; ++pc)
;             if ((pc * 2 * NM) / NLD == slot && pre) issue_piece(kt + DIST, pc);
;           __builtin_amdgcn_sched_barrier(0);
;         }
;       }
;     }
;   }
	s_waitcnt lgkmcnt(0)
	v_mfma_f32_32x32x16_bf16 v[16:31], v[76:79], v[84:87], v[16:31]
	v_mfma_f32_32x32x16_bf16 v[0:15], v[76:79], v[80:83], v[0:15]
	ds_read_b128 v[76:79], v37 offset:49152
	ds_read_b128 v[80:83], v37 offset:53248
	ds_read_b128 v[84:87], v51
	s_waitcnt lgkmcnt(0)
	v_mfma_f32_32x32x16_bf16 v[16:31], v[84:87], v[76:79], v[16:31]
	s_mov_b32 m0, s25
	v_lshl_add_u64 v[76:77], v[32:33], 0, s[70:71]
	s_mov_b64 s[26:27], 0x20300
	v_lshl_add_u64 v[78:79], v[32:33], 0, s[26:27]
	global_load_lds_dwordx4 v[76:77], off
	s_mov_b32 m0, s24
	s_nop 0
	global_load_lds_dwordx4 v[78:79], off
	v_mfma_f32_32x32x16_bf16 v[0:15], v[84:87], v[80:83], v[0:15]
	s_mov_b64 s[26:27], 0x40300
	v_lshl_add_u64 v[76:77], v[32:33], 0, s[26:27]
	s_mov_b32 m0, s23
	s_nop 0
	global_load_lds_dwordx4 v[76:77], off
	ds_read_b128 v[76:79], v58
	ds_read_b128 v[80:83], v38 offset:49152
	ds_read_b128 v[84:87], v38 offset:53248
	s_waitcnt lgkmcnt(0)
	v_mfma_f32_32x32x16_bf16 v[16:31], v[76:79], v[80:83], v[16:31]
	s_mov_b64 s[26:27], 0x60300
	v_lshl_add_u64 v[80:81], v[32:33], 0, s[26:27]
	s_mov_b32 m0, s22
	s_nop 0
	global_load_lds_dwordx4 v[80:81], off
	v_mfma_f32_32x32x16_bf16 v[0:15], v[76:79], v[84:87], v[0:15]
	s_mov_b32 m0, s21
	s_nop 0
	global_load_lds_dwordx4 v[88:89], off
	ds_read_b128 v[76:79], v40 offset:49152
	ds_read_b128 v[80:83], v40 offset:53248
	ds_read_b128 v[84:87], v60
	v_lshl_add_u64 v[88:89], v[34:35], 0, s[36:37]
	s_waitcnt lgkmcnt(0)
	v_mfma_f32_32x32x16_bf16 v[16:31], v[84:87], v[76:79], v[16:31]
	ds_read_b128 v[76:79], v61
	v_mfma_f32_32x32x16_bf16 v[0:15], v[84:87], v[80:83], v[0:15]
	ds_read_b128 v[80:83], v43 offset:53248
	ds_read_b128 v[84:87], v43 offset:49152
	s_waitcnt vmcnt(5)
	s_barrier
	s_waitcnt lgkmcnt(0)
	v_mfma_f32_32x32x16_bf16 v[16:31], v[76:79], v[84:87], v[16:31]
	v_mfma_f32_32x32x16_bf16 v[0:15], v[76:79], v[80:83], v[0:15]
	ds_read_b128 v[76:79], v62
	ds_read_b128 v[80:83], v62 offset:4096
	ds_read_b128 v[84:87], v63
	s_waitcnt lgkmcnt(0)
	v_mfma_f32_32x32x16_bf16 v[16:31], v[84:87], v[76:79], v[16:31]
	s_mov_b32 m0, s20
	v_lshl_add_u64 v[76:77], v[32:33], 0, s[36:37]
	s_mov_b64 s[26:27], 0x20380
	v_lshl_add_u64 v[78:79], v[32:33], 0, s[26:27]
	global_load_lds_dwordx4 v[76:77], off
	s_mov_b32 m0, s19
	s_nop 0
	global_load_lds_dwordx4 v[78:79], off
	v_mfma_f32_32x32x16_bf16 v[0:15], v[84:87], v[80:83], v[0:15]
	s_mov_b64 s[26:27], 0x40380
	v_lshl_add_u64 v[76:77], v[32:33], 0, s[26:27]
	s_mov_b32 m0, s18
	s_nop 0
	global_load_lds_dwordx4 v[76:77], off
	ds_read_b128 v[76:79], v67
	ds_read_b128 v[80:83], v66
	ds_read_b128 v[84:87], v66 offset:4096
	s_waitcnt lgkmcnt(0)
	v_mfma_f32_32x32x16_bf16 v[16:31], v[76:79], v[80:83], v[16:31]
	s_mov_b64 s[26:27], 0x60380
	v_lshl_add_u64 v[80:81], v[32:33], 0, s[26:27]
	s_mov_b32 m0, s13
	s_nop 0
	global_load_lds_dwordx4 v[80:81], off
	v_mfma_f32_32x32x16_bf16 v[0:15], v[76:79], v[84:87], v[0:15]
	s_mov_b32 m0, s12
	s_nop 0
	global_load_lds_dwordx4 v[88:89], off
	ds_read_b128 v[76:79], v64
	ds_read_b128 v[80:83], v64 offset:4096
	ds_read_b128 v[84:87], v72
	v_lshl_add_u64 v[88:89], v[34:35], 0, s[54:55]
	s_waitcnt lgkmcnt(0)
	v_mfma_f32_32x32x16_bf16 v[16:31], v[84:87], v[76:79], v[16:31]
	ds_read_b128 v[76:79], v74
	v_mfma_f32_32x32x16_bf16 v[0:15], v[84:87], v[80:83], v[0:15]
	ds_read_b128 v[80:83], v73 offset:4096
	ds_read_b128 v[84:87], v73
	s_waitcnt vmcnt(5)
	s_barrier
	s_waitcnt lgkmcnt(0)
	v_mfma_f32_32x32x16_bf16 v[16:31], v[76:79], v[84:87], v[16:31]
	v_mfma_f32_32x32x16_bf16 v[0:15], v[76:79], v[80:83], v[0:15]
	ds_read_b128 v[76:79], v37
	ds_read_b128 v[80:83], v37 offset:4096
	ds_read_b128 v[84:87], v36 offset:32768
	s_waitcnt lgkmcnt(0)
	v_mfma_f32_32x32x16_bf16 v[16:31], v[84:87], v[76:79], v[16:31]
	s_mov_b32 m0, s9
	v_lshl_add_u64 v[76:77], v[32:33], 0, s[54:55]
	s_mov_b64 s[26:27], 0x20400
	v_lshl_add_u64 v[78:79], v[32:33], 0, s[26:27]
	global_load_lds_dwordx4 v[76:77], off
	s_mov_b32 m0, s7
	s_nop 0
	global_load_lds_dwordx4 v[78:79], off
	v_mfma_f32_32x32x16_bf16 v[0:15], v[84:87], v[80:83], v[0:15]
	s_mov_b64 s[26:27], 0x40400
	v_lshl_add_u64 v[76:77], v[32:33], 0, s[26:27]
	s_mov_b32 m0, s8
	s_nop 0
	global_load_lds_dwordx4 v[76:77], off
	ds_read_b128 v[76:79], v39 offset:32768
	ds_read_b128 v[80:83], v38
	ds_read_b128 v[84:87], v38 offset:4096
	s_waitcnt lgkmcnt(0)
	v_mfma_f32_32x32x16_bf16 v[16:31], v[76:79], v[80:83], v[16:31]
	s_mov_b64 s[26:27], 0x60400
	v_lshl_add_u64 v[80:81], v[32:33], 0, s[26:27]
	s_mov_b32 m0, s10
	s_nop 0
	global_load_lds_dwordx4 v[80:81], off
	v_mfma_f32_32x32x16_bf16 v[0:15], v[76:79], v[84:87], v[0:15]
	s_mov_b32 m0, s11
	s_nop 0
	global_load_lds_dwordx4 v[88:89], off
	ds_read_b128 v[76:79], v40
	ds_read_b128 v[80:83], v40 offset:4096
	ds_read_b128 v[84:87], v41 offset:32768
	v_lshl_add_u64 v[88:89], v[34:35], 0, s[96:97]
	s_waitcnt lgkmcnt(0)
	v_mfma_f32_32x32x16_bf16 v[16:31], v[84:87], v[76:79], v[16:31]
	ds_read_b128 v[76:79], v42 offset:32768
	v_mfma_f32_32x32x16_bf16 v[0:15], v[84:87], v[80:83], v[0:15]
	ds_read_b128 v[80:83], v43 offset:4096
	ds_read_b128 v[84:87], v43
	s_waitcnt vmcnt(5)
	s_barrier
; #define MFMA(a, b, c) __builtin_amdgcn_mfma_f32_32x32x16_bf16((a), (b), (c), 0, 0, 0)
;     ...
;   for (int kt = 0; kt < nk; ++kt) {
;     if (DIST == 2 && kt + 1 < nk) {
;       if (NLD == 6) asm volatile("s_waitcnt vmcnt(6)" ::: "memory");
;       else if (NLD == 5) asm volatile("s_waitcnt vmcnt(5)" ::: "memory");
;       else asm volatile("s_waitcnt vmcnt(8)" ::: "memory");
;     } else {
;       asm volatile("s_waitcnt vmcnt(0)" ::: "memory");
;     }
;     __builtin_amdgcn_s_barrier();
;     const bool pre = (kt + DIST < nk);
;     const char* base = smem + (kt % NSTG) * STAGE;
;     const char* pa = base + (wrow_act + r) * 128;
;     const char* pw = base + ABYTES + (wrow_w + r) * 128;
;     constexpr int NM = NI * MJ;
;     constexpr int PPS = (NLD + 1) / 2;
; #pragma unroll
;     for (int s = 0; s < 4; ++s) {
;       bf16x8 af[MJ], wf[NI];
; #pragma unroll
;       for (int j = 0; j < MJ; ++j) af[j] = *(const bf16x8*)(pa + j * 32 * 128 + xo[s]);
; #pragma unroll
;       for (int i = 0; i < NI; ++i) wf[i] = *(const bf16x8*)(pw + i * 32 * 128 + xo[s]);
; #pragma unroll
;       for (int m = 0; m < NM; ++m) {
;         const int i = m / MJ, j = m % MJ;
;         acc[i][j] = MFMA(wf[i], af[j], acc[i][j]);
;         if (s < 2 && NM >= PPS) {
;           constexpr int EVERY = (NM / PPS) > 0 ? (NM / PPS) : 1;
;           if ((m + 1) % EVERY == 0) {
;             const int pc = s * PPS + (m + 1) / EVERY - 1;
;             if ((m + 1) / EVERY <= PPS && pc < NLD) {
;               __builtin_amdgcn_sched_barrier(0);
;               if (pre) issue_piece(kt + DIST, pc);
;               __builtin_amdgcn_sched_barrier(0);
;             }
;           }
;         }
;         if (s < 2 && NM < PPS) {
;           const int slot = s * NM + m;
;           __builtin_amdgcn_sched_barrier(0);
; #pragma unroll
;           for (int pc = 0; pc < NLD; ++pc)
;             if ((pc * 2 * NM) / NLD == slot && pre) issue_piece(kt + DIST, pc);
;           __builtin_amdgcn_sched_barrier(0);
;         }
;       }
;     }
;   }
	s_waitcnt lgkmcnt(0)
	v_mfma_f32_32x32x16_bf16 v[16:31], v[76:79], v[84:87], v[16:31]
	v_mfma_f32_32x32x16_bf16 v[0:15], v[76:79], v[80:83], v[0:15]
	ds_read_b128 v[76:79], v37 offset:49152
	ds_read_b128 v[80:83], v37 offset:53248
	ds_read_b128 v[84:87], v51
	s_waitcnt lgkmcnt(0)
	v_mfma_f32_32x32x16_bf16 v[16:31], v[84:87], v[76:79], v[16:31]
	s_mov_b32 m0, s25
	v_lshl_add_u64 v[76:77], v[32:33], 0, s[96:97]
	s_mov_b64 s[26:27], 0x20480
	v_lshl_add_u64 v[78:79], v[32:33], 0, s[26:27]
	global_load_lds_dwordx4 v[76:77], off
	s_mov_b32 m0, s24
	s_nop 0
	global_load_lds_dwordx4 v[78:79], off
	v_mfma_f32_32x32x16_bf16 v[0:15], v[84:87], v[80:83], v[0:15]
	s_mov_b64 s[24:25], 0x40480
	v_lshl_add_u64 v[76:77], v[32:33], 0, s[24:25]
	s_mov_b32 m0, s23
	s_nop 0
	global_load_lds_dwordx4 v[76:77], off
	ds_read_b128 v[76:79], v58
	ds_read_b128 v[80:83], v38 offset:49152
	ds_read_b128 v[84:87], v38 offset:53248
	s_waitcnt lgkmcnt(0)
	v_mfma_f32_32x32x16_bf16 v[16:31], v[76:79], v[80:83], v[16:31]
	s_mov_b64 s[24:25], 0x60480
	v_lshl_add_u64 v[80:81], v[32:33], 0, s[24:25]
	s_mov_b32 m0, s22
	s_nop 0
	global_load_lds_dwordx4 v[80:81], off
	v_mfma_f32_32x32x16_bf16 v[0:15], v[76:79], v[84:87], v[0:15]
	s_mov_b32 m0, s21
	s_nop 0
	global_load_lds_dwordx4 v[88:89], off
	ds_read_b128 v[76:79], v40 offset:49152
	ds_read_b128 v[80:83], v40 offset:53248
	ds_read_b128 v[84:87], v60
	v_lshl_add_u64 v[88:89], v[34:35], 0, s[30:31]
	s_waitcnt lgkmcnt(0)
	v_mfma_f32_32x32x16_bf16 v[16:31], v[84:87], v[76:79], v[16:31]
	ds_read_b128 v[76:79], v61
	v_mfma_f32_32x32x16_bf16 v[0:15], v[84:87], v[80:83], v[0:15]
	ds_read_b128 v[80:83], v43 offset:53248
	ds_read_b128 v[84:87], v43 offset:49152
	s_waitcnt vmcnt(5)
	s_barrier
	s_waitcnt lgkmcnt(0)
	v_mfma_f32_32x32x16_bf16 v[16:31], v[76:79], v[84:87], v[16:31]
	v_mfma_f32_32x32x16_bf16 v[0:15], v[76:79], v[80:83], v[0:15]
	ds_read_b128 v[76:79], v62
	ds_read_b128 v[80:83], v62 offset:4096
	ds_read_b128 v[84:87], v63
	s_waitcnt lgkmcnt(0)
	v_mfma_f32_32x32x16_bf16 v[16:31], v[84:87], v[76:79], v[16:31]
	s_mov_b32 m0, s20
	v_lshl_add_u64 v[76:77], v[32:33], 0, s[30:31]
	s_mov_b64 s[20:21], 0x20500
	v_lshl_add_u64 v[78:79], v[32:33], 0, s[20:21]
	global_load_lds_dwordx4 v[76:77], off
	s_mov_b32 m0, s19
	s_nop 0
	global_load_lds_dwordx4 v[78:79], off
	v_mfma_f32_32x32x16_bf16 v[0:15], v[84:87], v[80:83], v[0:15]
	s_mov_b64 s[20:21], 0x40500
	v_lshl_add_u64 v[76:77], v[32:33], 0, s[20:21]
	s_mov_b32 m0, s18
	s_nop 0
	global_load_lds_dwordx4 v[76:77], off
	ds_read_b128 v[76:79], v67
	ds_read_b128 v[80:83], v66
	ds_read_b128 v[84:87], v66 offset:4096
	s_waitcnt lgkmcnt(0)
	v_mfma_f32_32x32x16_bf16 v[16:31], v[76:79], v[80:83], v[16:31]
	s_mov_b64 s[18:19], 0x60500
	v_lshl_add_u64 v[80:81], v[32:33], 0, s[18:19]
	s_mov_b32 m0, s13
	s_nop 0
	global_load_lds_dwordx4 v[80:81], off
	v_mfma_f32_32x32x16_bf16 v[0:15], v[76:79], v[84:87], v[0:15]
	s_mov_b32 m0, s12
	s_nop 0
	global_load_lds_dwordx4 v[88:89], off
	ds_read_b128 v[76:79], v64
	ds_read_b128 v[80:83], v64 offset:4096
	ds_read_b128 v[84:87], v72
	v_lshl_add_u64 v[88:89], v[34:35], 0, s[84:85]
	s_waitcnt lgkmcnt(0)
	v_mfma_f32_32x32x16_bf16 v[16:31], v[84:87], v[76:79], v[16:31]
	ds_read_b128 v[76:79], v74
	v_mfma_f32_32x32x16_bf16 v[0:15], v[84:87], v[80:83], v[0:15]
	ds_read_b128 v[80:83], v73 offset:4096
	ds_read_b128 v[84:87], v73
	s_waitcnt vmcnt(5)
	s_barrier
	s_waitcnt lgkmcnt(0)
	v_mfma_f32_32x32x16_bf16 v[16:31], v[76:79], v[84:87], v[16:31]
	v_mfma_f32_32x32x16_bf16 v[0:15], v[76:79], v[80:83], v[0:15]
	ds_read_b128 v[76:79], v37
	ds_read_b128 v[80:83], v37 offset:4096
	ds_read_b128 v[84:87], v36 offset:32768
	s_waitcnt lgkmcnt(0)
	v_mfma_f32_32x32x16_bf16 v[16:31], v[84:87], v[76:79], v[16:31]
	s_mov_b32 m0, s9
	v_lshl_add_u64 v[76:77], v[32:33], 0, s[84:85]
	s_mov_b64 s[12:13], 0x20580
	v_lshl_add_u64 v[78:79], v[32:33], 0, s[12:13]
	global_load_lds_dwordx4 v[76:77], off
	s_mov_b32 m0, s7
	s_nop 0
	global_load_lds_dwordx4 v[78:79], off
	v_mfma_f32_32x32x16_bf16 v[0:15], v[84:87], v[80:83], v[0:15]
	s_mov_b64 s[12:13], 0x40580
	v_lshl_add_u64 v[76:77], v[32:33], 0, s[12:13]
	s_mov_b32 m0, s8
	s_nop 0
	global_load_lds_dwordx4 v[76:77], off
	ds_read_b128 v[76:79], v39 offset:32768
	ds_read_b128 v[80:83], v38
	ds_read_b128 v[84:87], v38 offset:4096
	s_waitcnt lgkmcnt(0)
	v_mfma_f32_32x32x16_bf16 v[16:31], v[76:79], v[80:83], v[16:31]
	s_mov_b64 s[8:9], 0x60580
	v_lshl_add_u64 v[80:81], v[32:33], 0, s[8:9]
	s_mov_b32 m0, s10
	s_nop 0
	global_load_lds_dwordx4 v[80:81], off
	v_mfma_f32_32x32x16_bf16 v[0:15], v[76:79], v[84:87], v[0:15]
	s_mov_b32 m0, s11
	s_nop 0
	global_load_lds_dwordx4 v[88:89], off
	ds_read_b128 v[76:79], v40
	ds_read_b128 v[80:83], v40 offset:4096
	ds_read_b128 v[84:87], v41 offset:32768
	v_lshl_add_u64 v[88:89], v[34:35], 0, s[38:39]
	s_waitcnt lgkmcnt(0)
	v_mfma_f32_32x32x16_bf16 v[16:31], v[84:87], v[76:79], v[16:31]
	ds_read_b128 v[76:79], v42 offset:32768
	v_mfma_f32_32x32x16_bf16 v[0:15], v[84:87], v[80:83], v[0:15]
	ds_read_b128 v[80:83], v43 offset:4096
	ds_read_b128 v[84:87], v43
	s_waitcnt vmcnt(5)
	s_barrier
; #define MFMA(a, b, c) __builtin_amdgcn_mfma_f32_32x32x16_bf16((a), (b), (c), 0, 0, 0)
;     ...
;   for (int kt = 0; kt < nk; ++kt) {
;     if (DIST == 2 && kt + 1 < nk) {
;       if (NLD == 6) asm volatile("s_waitcnt vmcnt(6)" ::: "memory");
;       else if (NLD == 5) asm volatile("s_waitcnt vmcnt(5)" ::: "memory");
;       else asm volatile("s_waitcnt vmcnt(8)" ::: "memory");
;     } else {
;       asm volatile("s_waitcnt vmcnt(0)" ::: "memory");
;     }
;     __builtin_amdgcn_s_barrier();
;     const bool pre = (kt + DIST < nk);
;     const char* base = smem + (kt % NSTG) * STAGE;
;     const char* pa = base + (wrow_act + r) * 128;
;     const char* pw = base + ABYTES + (wrow_w + r) * 128;
;     constexpr int NM = NI * MJ;
;     constexpr int PPS = (NLD + 1) / 2;
; #pragma unroll
;     for (int s = 0; s < 4; ++s) {
;       bf16x8 af[MJ], wf[NI];
; #pragma unroll
;       for (int j = 0; j < MJ; ++j) af[j] = *(const bf16x8*)(pa + j * 32 * 128 + xo[s]);
; #pragma unroll
;       for (int i = 0; i < NI; ++i) wf[i] = *(const bf16x8*)(pw + i * 32 * 128 + xo[s]);
; #pragma unroll
;       for (int m = 0; m < NM; ++m) {
;         const int i = m / MJ, j = m % MJ;
;         acc[i][j] = MFMA(wf[i], af[j], acc[i][j]);
;         if (s < 2 && NM >= PPS) {
;           constexpr int EVERY = (NM / PPS) > 0 ? (NM / PPS) : 1;
;           if ((m + 1) % EVERY == 0) {
;             const int pc = s * PPS + (m + 1) / EVERY - 1;
;             if ((m + 1) / EVERY <= PPS && pc < NLD) {
;               __builtin_amdgcn_sched_barrier(0);
;               if (pre) issue_piece(kt + DIST, pc);
;               __builtin_amdgcn_sched_barrier(0);
;             }
;           }
;         }
;         if (s < 2 && NM < PPS) {
;           const int slot = s * NM + m;
;           __builtin_amdgcn_sched_barrier(0);
; #pragma unroll
;           for (int pc = 0; pc < NLD; ++pc)
;             if ((pc * 2 * NM) / NLD == slot && pre) issue_piece(kt + DIST, pc);
;           __builtin_amdgcn_sched_barrier(0);
;         }
;       }
;     }
;   }
	s_waitcnt lgkmcnt(0)
	v_mfma_f32_32x32x16_bf16 v[16:31], v[76:79], v[84:87], v[16:31]
	v_mfma_f32_32x32x16_bf16 v[0:15], v[76:79], v[80:83], v[0:15]
	ds_read_b128 v[76:79], v37 offset:49152
	ds_read_b128 v[80:83], v37 offset:53248
	ds_read_b128 v[84:87], v51
	s_waitcnt lgkmcnt(0)
	v_mfma_f32_32x32x16_bf16 v[16:31], v[84:87], v[76:79], v[16:31]
	v_readfirstlane_b32 s10, v70
	v_lshl_add_u64 v[76:77], v[32:33], 0, s[38:39]
	s_mov_b64 s[8:9], 0x20600
	s_mov_b32 m0, s10
	v_readfirstlane_b32 s7, v71
	v_lshl_add_u64 v[78:79], v[32:33], 0, s[8:9]
	global_load_lds_dwordx4 v[76:77], off
	s_mov_b32 m0, s7
	s_nop 0
	global_load_lds_dwordx4 v[78:79], off
	ds_read_b128 v[76:79], v58
	v_mfma_f32_32x32x16_bf16 v[0:15], v[84:87], v[80:83], v[0:15]
	s_mov_b64 s[8:9], 0x40600
	v_lshl_add_u64 v[70:71], v[32:33], 0, s[8:9]
	v_readfirstlane_b32 s8, v69
	s_mov_b32 m0, s8
	s_nop 0
	global_load_lds_dwordx4 v[70:71], off
	ds_read_b128 v[80:83], v38 offset:49152
	ds_read_b128 v[84:87], v38 offset:53248
	s_waitcnt lgkmcnt(0)
	v_mfma_f32_32x32x16_bf16 v[16:31], v[76:79], v[80:83], v[16:31]
	s_mov_b64 s[12:13], 0x60600
	v_readfirstlane_b32 s9, v68
	v_lshl_add_u64 v[70:71], v[32:33], 0, s[12:13]
	s_mov_b32 m0, s9
	s_nop 0
	global_load_lds_dwordx4 v[70:71], off
	ds_read_b128 v[68:71], v40 offset:49152
	v_mfma_f32_32x32x16_bf16 v[0:15], v[76:79], v[84:87], v[0:15]
	v_readfirstlane_b32 s11, v65
	s_mov_b32 m0, s11
	s_nop 0
	global_load_lds_dwordx4 v[88:89], off
	ds_read_b128 v[76:79], v40 offset:53248
	ds_read_b128 v[80:83], v60
	v_lshl_add_u64 v[84:85], v[34:35], 0, s[68:69]
	s_waitcnt lgkmcnt(0)
	v_mfma_f32_32x32x16_bf16 v[16:31], v[80:83], v[68:71], v[16:31]
	ds_read_b128 v[68:71], v61
	v_mfma_f32_32x32x16_bf16 v[0:15], v[80:83], v[76:79], v[0:15]
	ds_read_b128 v[76:79], v43 offset:53248
	ds_read_b128 v[80:83], v43 offset:49152
	s_waitcnt vmcnt(5)
	s_barrier
	s_waitcnt lgkmcnt(0)
	v_mfma_f32_32x32x16_bf16 v[16:31], v[68:71], v[80:83], v[16:31]
	v_mfma_f32_32x32x16_bf16 v[0:15], v[68:71], v[76:79], v[0:15]
	ds_read_b128 v[68:71], v62
	ds_read_b128 v[76:79], v62 offset:4096
	ds_read_b128 v[80:83], v63
	s_waitcnt lgkmcnt(0)
	v_mfma_f32_32x32x16_bf16 v[16:31], v[80:83], v[68:71], v[16:31]
	s_mov_b64 s[12:13], 0x20680
	v_lshl_add_u64 v[70:71], v[32:33], 0, s[12:13]
	v_readfirstlane_b32 s12, v56
	v_lshl_add_u64 v[68:69], v[32:33], 0, s[68:69]
	s_mov_b32 m0, s12
	v_readfirstlane_b32 s12, v59
	global_load_lds_dwordx4 v[68:69], off
	s_mov_b32 m0, s12
	s_nop 0
	global_load_lds_dwordx4 v[70:71], off
	v_mfma_f32_32x32x16_bf16 v[0:15], v[80:83], v[76:79], v[0:15]
	s_mov_b64 s[12:13], 0x40680
	v_lshl_add_u64 v[68:69], v[32:33], 0, s[12:13]
	v_readfirstlane_b32 s12, v57
	s_mov_b32 m0, s12
	s_nop 0
	global_load_lds_dwordx4 v[68:69], off
	ds_read_b128 v[68:71], v67
	ds_read_b128 v[76:79], v66
	ds_read_b128 v[80:83], v66 offset:4096
	s_waitcnt lgkmcnt(0)
	v_mfma_f32_32x32x16_bf16 v[16:31], v[68:71], v[76:79], v[16:31]
	v_readfirstlane_b32 s12, v50
	v_lshl_add_u64 v[56:57], v[32:33], 0, s[58:59]
	s_mov_b32 m0, s12
	s_nop 0
	global_load_lds_dwordx4 v[56:57], off
	v_mfma_f32_32x32x16_bf16 v[0:15], v[68:71], v[80:83], v[0:15]
	v_readfirstlane_b32 s12, v49
	s_mov_b32 m0, s12
	s_nop 0
	global_load_lds_dwordx4 v[84:85], off
	ds_read_b128 v[68:71], v64
	ds_read_b128 v[76:79], v64 offset:4096
	ds_read_b128 v[80:83], v72
	v_lshl_add_u64 v[56:57], v[34:35], 0, s[60:61]
	s_waitcnt lgkmcnt(0)
	v_mfma_f32_32x32x16_bf16 v[16:31], v[80:83], v[68:71], v[16:31]
	ds_read_b128 v[68:71], v74
	v_mfma_f32_32x32x16_bf16 v[0:15], v[80:83], v[76:79], v[0:15]
	ds_read_b128 v[76:79], v73 offset:4096
	ds_read_b128 v[80:83], v73
	s_waitcnt vmcnt(5)
	s_barrier
	s_waitcnt lgkmcnt(0)
	v_mfma_f32_32x32x16_bf16 v[16:31], v[68:71], v[80:83], v[16:31]
	v_mfma_f32_32x32x16_bf16 v[0:15], v[68:71], v[76:79], v[0:15]
	ds_read_b128 v[68:71], v37
	ds_read_b128 v[76:79], v37 offset:4096
	ds_read_b128 v[80:83], v36 offset:32768
	s_waitcnt lgkmcnt(0)
	v_mfma_f32_32x32x16_bf16 v[16:31], v[80:83], v[68:71], v[16:31]
	v_readfirstlane_b32 s12, v44
	v_lshl_add_u64 v[68:69], v[32:33], 0, s[60:61]
	s_mov_b32 m0, s12
	v_readfirstlane_b32 s12, v45
	v_lshl_add_u64 v[70:71], v[32:33], 0, s[90:91]
	global_load_lds_dwordx4 v[68:69], off
	s_mov_b32 m0, s12
	s_nop 0
	global_load_lds_dwordx4 v[70:71], off
	ds_read_b128 v[68:71], v39 offset:32768
	v_mfma_f32_32x32x16_bf16 v[0:15], v[80:83], v[76:79], v[0:15]
	v_readfirstlane_b32 s12, v46
	v_lshl_add_u64 v[44:45], v[32:33], 0, vcc
	s_mov_b32 m0, s12
	s_nop 0
	global_load_lds_dwordx4 v[44:45], off
	ds_read_b128 v[76:79], v38
	ds_read_b128 v[80:83], v38 offset:4096
	s_waitcnt lgkmcnt(0)
	v_mfma_f32_32x32x16_bf16 v[16:31], v[68:71], v[76:79], v[16:31]
	v_readfirstlane_b32 s12, v47
	v_lshl_add_u64 v[44:45], v[32:33], 0, s[28:29]
	s_mov_b32 m0, s12
	s_nop 0
	global_load_lds_dwordx4 v[44:45], off
	ds_read_b128 v[44:47], v41 offset:32768
	v_mfma_f32_32x32x16_bf16 v[0:15], v[68:71], v[80:83], v[0:15]
	v_readfirstlane_b32 s12, v48
	s_mov_b32 m0, s12
	s_nop 0
	global_load_lds_dwordx4 v[56:57], off
	ds_read_b128 v[68:71], v40
	v_lshl_add_u64 v[34:35], v[34:35], 0, s[46:47]
	s_waitcnt lgkmcnt(0)
	v_mfma_f32_32x32x16_bf16 v[16:31], v[44:47], v[68:71], v[16:31]
	ds_read_b128 v[68:71], v40 offset:4096
	s_waitcnt lgkmcnt(0)
	v_mfma_f32_32x32x16_bf16 v[0:15], v[44:47], v[68:71], v[0:15]
	ds_read_b128 v[44:47], v42 offset:32768
	ds_read_b128 v[68:71], v43
	s_waitcnt lgkmcnt(0)
	v_mfma_f32_32x32x16_bf16 v[16:31], v[44:47], v[68:71], v[16:31]
	ds_read_b128 v[68:71], v43 offset:4096
	s_waitcnt vmcnt(5)
	s_barrier
; #define MFMA(a, b, c) __builtin_amdgcn_mfma_f32_32x32x16_bf16((a), (b), (c), 0, 0, 0)
;     ...
;   for (int kt = 0; kt < nk; ++kt) {
;     if (DIST == 2 && kt + 1 < nk) {
;       if (NLD == 6) asm volatile("s_waitcnt vmcnt(6)" ::: "memory");
;       else if (NLD == 5) asm volatile("s_waitcnt vmcnt(5)" ::: "memory");
;       else asm volatile("s_waitcnt vmcnt(8)" ::: "memory");
;     } else {
;       asm volatile("s_waitcnt vmcnt(0)" ::: "memory");
;     }
;     __builtin_amdgcn_s_barrier();
;     const bool pre = (kt + DIST < nk);
;     const char* base = smem + (kt % NSTG) * STAGE;
;     const char* pa = base + (wrow_act + r) * 128;
;     const char* pw = base + ABYTES + (wrow_w + r) * 128;
;     constexpr int NM = NI * MJ;
;     constexpr int PPS = (NLD + 1) / 2;
; #pragma unroll
;     for (int s = 0; s < 4; ++s) {
;       bf16x8 af[MJ], wf[NI];
; #pragma unroll
;       for (int j = 0; j < MJ; ++j) af[j] = *(const bf16x8*)(pa + j * 32 * 128 + xo[s]);
; #pragma unroll
;       for (int i = 0; i < NI; ++i) wf[i] = *(const bf16x8*)(pw + i * 32 * 128 + xo[s]);
; #pragma unroll
;       for (int m = 0; m < NM; ++m) {
;         const int i = m / MJ, j = m % MJ;
;         acc[i][j] = MFMA(wf[i], af[j], acc[i][j]);
;         if (s < 2 && NM >= PPS) {
;           constexpr int EVERY = (NM / PPS) > 0 ? (NM / PPS) : 1;
;           if ((m + 1) % EVERY == 0) {
;             const int pc = s * PPS + (m + 1) / EVERY - 1;
;             if ((m + 1) / EVERY <= PPS && pc < NLD) {
;               __builtin_amdgcn_sched_barrier(0);
;               if (pre) issue_piece(kt + DIST, pc);
;               __builtin_amdgcn_sched_barrier(0);
;             }
;           }
;         }
;         if (s < 2 && NM < PPS) {
;           const int slot = s * NM + m;
;           __builtin_amdgcn_sched_barrier(0);
; #pragma unroll
;           for (int pc = 0; pc < NLD; ++pc)
;             if ((pc * 2 * NM) / NLD == slot && pre) issue_piece(kt + DIST, pc);
;           __builtin_amdgcn_sched_barrier(0);
;         }
;       }
;     }
;   }
;   __builtin_amdgcn_s_barrier();
	s_waitcnt lgkmcnt(0)
	v_mfma_f32_32x32x16_bf16 v[0:15], v[44:47], v[68:71], v[0:15]
	ds_read_b128 v[44:47], v51
	ds_read_b128 v[48:51], v37 offset:49152
	ds_read_b128 v[68:71], v37 offset:53248
	s_waitcnt lgkmcnt(0)
	v_mfma_f32_32x32x16_bf16 v[16:31], v[44:47], v[48:51], v[16:31]
	s_mov_b32 m0, s10
	v_lshl_add_u64 v[48:49], v[32:33], 0, s[46:47]
	v_lshl_add_u64 v[50:51], v[32:33], 0, s[48:49]
	global_load_lds_dwordx4 v[48:49], off
	s_mov_b32 m0, s7
	s_nop 0
	global_load_lds_dwordx4 v[50:51], off
	v_mfma_f32_32x32x16_bf16 v[0:15], v[44:47], v[68:71], v[0:15]
	v_lshl_add_u64 v[44:45], v[32:33], 0, s[50:51]
	s_mov_b32 m0, s8
	s_nop 0
	global_load_lds_dwordx4 v[44:45], off
	ds_read_b128 v[44:47], v58
	ds_read_b128 v[48:51], v38 offset:49152
	ds_read_b128 v[56:59], v38 offset:53248
	s_waitcnt lgkmcnt(0)
	v_mfma_f32_32x32x16_bf16 v[16:31], v[44:47], v[48:51], v[16:31]
	v_lshl_add_u64 v[32:33], v[32:33], 0, s[86:87]
	s_mov_b32 m0, s9
	s_nop 0
	global_load_lds_dwordx4 v[32:33], off
	v_mfma_f32_32x32x16_bf16 v[0:15], v[44:47], v[56:59], v[0:15]
	s_mov_b32 m0, s11
	s_nop 0
	global_load_lds_dwordx4 v[34:35], off
	ds_read_b128 v[32:35], v60
	ds_read_b128 v[44:47], v40 offset:49152
	s_waitcnt lgkmcnt(0)
	v_mfma_f32_32x32x16_bf16 v[16:31], v[32:35], v[44:47], v[16:31]
	ds_read_b128 v[44:47], v40 offset:53248
	s_waitcnt lgkmcnt(0)
	v_mfma_f32_32x32x16_bf16 v[0:15], v[32:35], v[44:47], v[0:15]
	ds_read_b128 v[32:35], v61
	ds_read_b128 v[44:47], v43 offset:49152
	s_waitcnt lgkmcnt(0)
	v_mfma_f32_32x32x16_bf16 v[16:31], v[32:35], v[44:47], v[16:31]
	ds_read_b128 v[44:47], v43 offset:53248
	s_waitcnt vmcnt(5)
	s_barrier
	s_waitcnt lgkmcnt(0)
	v_mfma_f32_32x32x16_bf16 v[0:15], v[32:35], v[44:47], v[0:15]
	ds_read_b128 v[32:35], v63
	ds_read_b128 v[44:47], v62
	ds_read_b128 v[48:51], v62 offset:4096
	s_waitcnt lgkmcnt(0)
	v_mfma_f32_32x32x16_bf16 v[16:31], v[32:35], v[44:47], v[16:31]
	v_mfma_f32_32x32x16_bf16 v[0:15], v[32:35], v[48:51], v[0:15]
	ds_read_b128 v[32:35], v67
	ds_read_b128 v[44:47], v66
	ds_read_b128 v[48:51], v66 offset:4096
	s_waitcnt lgkmcnt(0)
	v_mfma_f32_32x32x16_bf16 v[16:31], v[32:35], v[44:47], v[16:31]
	v_mfma_f32_32x32x16_bf16 v[0:15], v[32:35], v[48:51], v[0:15]
	ds_read_b128 v[32:35], v72
	ds_read_b128 v[44:47], v64
	s_waitcnt lgkmcnt(0)
	v_mfma_f32_32x32x16_bf16 v[16:31], v[32:35], v[44:47], v[16:31]
	ds_read_b128 v[44:47], v64 offset:4096
	s_waitcnt lgkmcnt(0)
	v_mfma_f32_32x32x16_bf16 v[0:15], v[32:35], v[44:47], v[0:15]
	ds_read_b128 v[32:35], v74
	ds_read_b128 v[44:47], v73
	s_waitcnt lgkmcnt(0)
	v_mfma_f32_32x32x16_bf16 v[16:31], v[32:35], v[44:47], v[16:31]
	ds_read_b128 v[44:47], v73 offset:4096
	s_waitcnt vmcnt(0)
	s_barrier
	s_waitcnt lgkmcnt(0)
	v_mfma_f32_32x32x16_bf16 v[0:15], v[32:35], v[44:47], v[0:15]
	ds_read_b128 v[32:35], v36 offset:32768
	ds_read_b128 v[44:47], v37
	ds_read_b128 v[48:51], v37 offset:4096
	s_waitcnt lgkmcnt(0)
	v_mfma_f32_32x32x16_bf16 v[16:31], v[32:35], v[44:47], v[16:31]
	v_mfma_f32_32x32x16_bf16 v[0:15], v[32:35], v[48:51], v[0:15]
	ds_read_b128 v[32:35], v39 offset:32768
	ds_read_b128 v[44:47], v38
	ds_read_b128 v[36:39], v38 offset:4096
	s_waitcnt lgkmcnt(0)
	v_mfma_f32_32x32x16_bf16 v[16:31], v[32:35], v[44:47], v[16:31]
	v_mfma_f32_32x32x16_bf16 v[0:15], v[32:35], v[36:39], v[0:15]
	ds_read_b128 v[32:35], v40
	ds_read_b128 v[36:39], v40 offset:4096
	ds_read_b128 v[44:47], v41 offset:32768
	s_mulk_i32 s6, 0x2100
	v_lshl_or_b32 v144, s5, 8, v55
	v_lshl_add_u64 v[56:57], s[0:1], 0, v[144:145]
	s_add_i32 s3, s3, s2
	s_waitcnt lgkmcnt(0)
	v_mfma_f32_32x32x16_bf16 v[0:15], v[44:47], v[36:39], v[0:15]
	s_cmp_lt_i32 s3, 32
	v_mfma_f32_32x32x16_bf16 v[16:31], v[44:47], v[32:35], v[16:31]
	ds_read_b128 v[32:35], v42 offset:32768
	ds_read_b128 v[36:39], v43 offset:4096
	ds_read_b128 v[40:43], v43
	s_barrier
; DEV void phase_outproj(const Params& p, int l, int hf, char* smem) {
;     ...
;       const float* gate = mod + 4 * 3072 + 2048;
; #pragma unroll
;       for (int j = 0; j < 2; ++j) {
;         const int m = mt * 256 + wm * 64 + 32 * j + r;
;         const int bl = m / TP, tp = m - bl * TP;
;         float* dst = (float*)(ws + OFF_CTX1) + ((size_t)(hf * 2 + bl) * CTXL + tp) * DM;
; #pragma unroll
;         for (int g4 = 0; g4 < 4; ++g4) {
;           const int n = nt64 * 64 + wn * 32 + 8 * g4 + 4 * h;
;           const float4 xv = *(const float4*)(p.ctx + ((size_t)(hf * 2 + bl) * CTXL + tp) * DM + n);
;           const float4 gv = *(const float4*)(gate + n);
;           float4 o;
;           o.x = xv.x + gv.x * acc[0][j][4 * g4];
;           o.y = xv.y + gv.y * acc[0][j][4 * g4 + 1];
;           o.z = xv.z + gv.z * acc[0][j][4 * g4 + 2];
;           o.w = xv.w + gv.w * acc[0][j][4 * g4 + 3];
;           *(float4*)(dst + n) = o;
;         }
;       }
	s_waitcnt lgkmcnt(0)
	v_mfma_f32_32x32x16_bf16 v[0:15], v[32:35], v[36:39], v[0:15]
	v_add_u32_e32 v38, s6, v54
	v_mfma_f32_32x32x16_bf16 v[16:31], v[32:35], v[40:43], v[16:31]
	v_mul_hi_i32 v32, v38, s72
	v_lshrrev_b32_e32 v33, 31, v32
	v_ashrrev_i32_e32 v32, 11, v32
	v_add_u32_e32 v33, v32, v33
	v_add_u32_e32 v34, s4, v33
	v_mad_i32_i24 v32, v33, s73, v38
	v_ashrrev_i32_e32 v35, 31, v34
	v_ashrrev_i32_e32 v33, 31, v32
	v_lshlrev_b64 v[34:35], 20, v[34:35]
	v_lshl_add_u64 v[36:37], s[40:41], 0, v[34:35]
	v_lshlrev_b64 v[32:33], 12, v[32:33]
	v_lshl_add_u64 v[34:35], s[44:45], 0, v[34:35]
	v_lshl_add_u64 v[36:37], v[36:37], 0, v[32:33]
	v_lshl_add_u64 v[32:33], v[34:35], 0, v[32:33]
	v_or_b32_e32 v34, 32, v38
	v_mul_hi_i32 v35, v34, s72
	v_lshrrev_b32_e32 v38, 31, v35
	v_ashrrev_i32_e32 v35, 11, v35
	v_add_u32_e32 v35, v35, v38
	v_add_u32_e32 v38, s4, v35
	v_lshl_add_u64 v[50:51], v[32:33], 0, v[144:145]
	v_or_b32_e32 v32, 32, v144
	v_mov_b32_e32 v33, v145
	v_mad_i32_i24 v34, v35, s73, v34
	v_ashrrev_i32_e32 v39, 31, v38
	v_lshl_add_u64 v[40:41], s[0:1], 0, v[32:33]
	v_or_b32_e32 v32, 64, v144
	v_ashrrev_i32_e32 v35, 31, v34
	v_lshlrev_b64 v[38:39], 20, v[38:39]
	v_lshl_add_u64 v[48:49], v[36:37], 0, v[144:145]
	v_lshl_add_u64 v[36:37], s[0:1], 0, v[32:33]
	v_or_b32_e32 v32, 0x60, v144
	v_lshl_add_u64 v[42:43], s[40:41], 0, v[38:39]
	v_lshlrev_b64 v[34:35], 12, v[34:35]
	v_lshl_add_u64 v[38:39], s[44:45], 0, v[38:39]
	v_lshl_add_u64 v[32:33], s[0:1], 0, v[32:33]
	v_lshl_add_u64 v[42:43], v[42:43], 0, v[34:35]
	v_lshl_add_u64 v[34:35], v[38:39], 0, v[34:35]
	v_lshl_add_u64 v[46:47], v[34:35], 0, v[144:145]
	v_lshl_add_u64 v[44:45], v[42:43], 0, v[144:145]
	s_waitcnt vmcnt(0)
	flat_load_dwordx4 v[32:35], v[32:33]
	s_nop 0
	flat_load_dwordx4 v[36:39], v[36:37]
	s_nop 0
	flat_load_dwordx4 v[40:43], v[40:41]
	s_nop 0
	flat_load_dwordx4 v[56:59], v[56:57]
	s_nop 0
	global_load_dwordx4 v[60:63], v[50:51], off
	s_waitcnt vmcnt(0) lgkmcnt(0)
	v_pk_fma_f32 v[16:17], v[16:17], v[56:57], v[60:61]
	v_pk_fma_f32 v[18:19], v[18:19], v[58:59], v[62:63]
	flat_store_dwordx4 v[48:49], v[16:19]
	global_load_dwordx4 v[16:19], v[50:51], off offset:32
	s_waitcnt vmcnt(0)
	v_pk_fma_f32 v[16:17], v[20:21], v[40:41], v[16:17]
	v_pk_fma_f32 v[18:19], v[22:23], v[42:43], v[18:19]
	flat_store_dwordx4 v[48:49], v[16:19] offset:32
	global_load_dwordx4 v[16:19], v[50:51], off offset:64
	s_waitcnt vmcnt(0)
	v_pk_fma_f32 v[16:17], v[24:25], v[36:37], v[16:17]
	v_pk_fma_f32 v[18:19], v[26:27], v[38:39], v[18:19]
	flat_store_dwordx4 v[48:49], v[16:19] offset:64
	global_load_dwordx4 v[16:19], v[50:51], off offset:96
	s_waitcnt vmcnt(0)
	v_pk_fma_f32 v[16:17], v[28:29], v[32:33], v[16:17]
	v_pk_fma_f32 v[18:19], v[30:31], v[34:35], v[18:19]
	flat_store_dwordx4 v[48:49], v[16:19] offset:96
	global_load_dwordx4 v[16:19], v[46:47], off
	s_waitcnt vmcnt(0)
	v_pk_fma_f32 v[0:1], v[0:1], v[56:57], v[16:17]
	v_pk_fma_f32 v[2:3], v[2:3], v[58:59], v[18:19]
	flat_store_dwordx4 v[44:45], v[0:3]
	global_load_dwordx4 v[0:3], v[46:47], off offset:32
	s_waitcnt vmcnt(0)
	v_pk_fma_f32 v[0:1], v[4:5], v[40:41], v[0:1]
	v_pk_fma_f32 v[2:3], v[6:7], v[42:43], v[2:3]
	flat_store_dwordx4 v[44:45], v[0:3] offset:32
	global_load_dwordx4 v[0:3], v[46:47], off offset:64
	s_waitcnt vmcnt(0)
	v_pk_fma_f32 v[0:1], v[8:9], v[36:37], v[0:1]
	v_pk_fma_f32 v[2:3], v[10:11], v[38:39], v[2:3]
	flat_store_dwordx4 v[44:45], v[0:3] offset:64
	global_load_dwordx4 v[0:3], v[46:47], off offset:96
	s_waitcnt vmcnt(0)
	v_pk_fma_f32 v[0:1], v[12:13], v[32:33], v[0:1]
	v_pk_fma_f32 v[2:3], v[14:15], v[34:35], v[2:3]
	flat_store_dwordx4 v[44:45], v[0:3] offset:96
	s_cbranch_scc1 .LBB0_31
